# scan step: both y partial pairs of an iteration in one ds_write2st64_b32; step-B operand reads issued early and waited for once
# speedup vs baseline: 1.0046x; 1.0016x over previous
.LBB0_415:
	v_swap_b32 v17, v12
	v_swap_b32 v19, v14
	s_waitcnt lgkmcnt(0)
	v_pk_mul_f32 v[132:133], v[16:17], v[32:33] op_sel_hi:[1,0]
	v_pk_fma_f32 v[132:133], v[12:13], v[32:33], v[132:133] op_sel:[0,1,0]
	v_pk_fma_f32 v[132:133], v[18:19], v[34:35], v[132:133] op_sel_hi:[1,0,1]
	v_pk_fma_f32 v[132:133], v[14:15], v[34:35], v[132:133] op_sel:[0,1,0]
	ds_read_b128 v[94:97], v42 offset:12288
	ds_read_b128 v[116:119], v42 offset:16384
	ds_read_b128 v[120:123], v42 offset:8192
	ds_read_b128 v[124:127], v42
	ds_read_b64 v[130:131], v92
	v_pk_fma_f32 v[16:17], v[28:29], v[90:91], v[16:17] op_sel_hi:[0,1,1]
	v_pk_fma_f32 v[12:13], v[28:29], v[90:91], v[12:13] op_sel:[1,0,0]
	v_add_f32_dpp v132, v132, v132 quad_perm:[1,0,3,2] row_mask:0xf bank_mask:0xf bound_ctrl:1
	v_add_f32_dpp v133, v133, v133 quad_perm:[1,0,3,2] row_mask:0xf bank_mask:0xf bound_ctrl:1
	v_pk_fma_f32 v[18:19], v[30:31], v[90:91], v[18:19] op_sel_hi:[0,1,1]
	v_add_f32_dpp v132, v132, v132 quad_perm:[2,3,0,1] row_mask:0xf bank_mask:0xf bound_ctrl:1
	v_add_f32_dpp v133, v133, v133 quad_perm:[2,3,0,1] row_mask:0xf bank_mask:0xf bound_ctrl:1
	v_pk_fma_f32 v[14:15], v[30:31], v[90:91], v[14:15] op_sel:[1,0,0]
	v_add_f32_dpp v132, v132, v132 row_half_mirror row_mask:0xf bank_mask:0xf bound_ctrl:1
	v_add_f32_dpp v133, v133, v133 row_half_mirror row_mask:0xf bank_mask:0xf bound_ctrl:1
	ds_read_b64 v[90:91], v115 offset:20736
	v_add_f32_dpp v132, v132, v132 row_mirror row_mask:0xf bank_mask:0xf bound_ctrl:1
	v_add_f32_dpp v133, v133, v133 row_mirror row_mask:0xf bank_mask:0xf bound_ctrl:1
	v_pk_fma_f32 v[16:17], v[24:25], v[132:133], v[16:17] op_sel_hi:[0,1,1]
	v_pk_fma_f32 v[12:13], v[24:25], v[132:133], v[12:13] op_sel:[1,0,0]
	v_pk_fma_f32 v[18:19], v[26:27], v[132:133], v[18:19] op_sel_hi:[0,1,1]
	v_pk_fma_f32 v[14:15], v[26:27], v[132:133], v[14:15] op_sel:[1,0,0]
	s_waitcnt lgkmcnt(1)
	v_pk_mul_f32 v[132:133], v[16:17], v[94:95] op_sel_hi:[1,0]
	v_pk_mul_f32 v[24:25], v[16:17], v[20:21] op_sel_hi:[1,0]
	v_pk_fma_f32 v[132:133], v[12:13], v[94:95], v[132:133] op_sel:[0,1,0]
	v_pk_fma_f32 v[24:25], v[12:13], v[20:21], v[24:25] op_sel:[0,1,0]
	v_pk_fma_f32 v[132:133], v[18:19], v[96:97], v[132:133] op_sel_hi:[1,0,1]
	v_pk_fma_f32 v[24:25], v[18:19], v[22:23], v[24:25] op_sel_hi:[1,0,1]
	v_pk_fma_f32 v[132:133], v[14:15], v[96:97], v[132:133] op_sel:[0,1,0]
	v_pk_fma_f32 v[24:25], v[14:15], v[22:23], v[24:25] op_sel:[0,1,0]
	v_cvt_pk_f16_f32 v96, v24, v25
	v_add_f32_dpp v132, v132, v132 quad_perm:[1,0,3,2] row_mask:0xf bank_mask:0xf bound_ctrl:1
	v_add_f32_dpp v133, v133, v133 quad_perm:[1,0,3,2] row_mask:0xf bank_mask:0xf bound_ctrl:1
	ds_read_b128 v[32:35], v114 offset:12800
	ds_read_b128 v[24:27], v114 offset:16896
	ds_read_b128 v[28:31], v114 offset:8704
	ds_read_b128 v[20:23], v114 offset:512
	v_pk_fma_f32 v[16:17], v[120:121], v[130:131], v[16:17] op_sel_hi:[0,1,1]
	v_add_f32_dpp v132, v132, v132 quad_perm:[2,3,0,1] row_mask:0xf bank_mask:0xf bound_ctrl:1
	v_add_f32_dpp v133, v133, v133 quad_perm:[2,3,0,1] row_mask:0xf bank_mask:0xf bound_ctrl:1
	v_pk_fma_f32 v[12:13], v[120:121], v[130:131], v[12:13] op_sel:[1,0,0]
	v_add_f32_dpp v132, v132, v132 row_half_mirror row_mask:0xf bank_mask:0xf bound_ctrl:1
	v_add_f32_dpp v133, v133, v133 row_half_mirror row_mask:0xf bank_mask:0xf bound_ctrl:1
	v_pk_fma_f32 v[18:19], v[122:123], v[130:131], v[18:19] op_sel_hi:[0,1,1]
	v_pk_fma_f32 v[14:15], v[122:123], v[130:131], v[14:15] op_sel:[1,0,0]
	v_add_f32_dpp v132, v132, v132 row_mirror row_mask:0xf bank_mask:0xf bound_ctrl:1
	v_add_f32_dpp v133, v133, v133 row_mirror row_mask:0xf bank_mask:0xf bound_ctrl:1
	v_pk_fma_f32 v[16:17], v[116:117], v[132:133], v[16:17] op_sel_hi:[0,1,1]
	v_pk_fma_f32 v[12:13], v[116:117], v[132:133], v[12:13] op_sel:[1,0,0]
	v_pk_fma_f32 v[18:19], v[118:119], v[132:133], v[18:19] op_sel_hi:[0,1,1]
	v_pk_fma_f32 v[14:15], v[118:119], v[132:133], v[14:15] op_sel:[1,0,0]
	s_waitcnt lgkmcnt(0)
	v_pk_mul_f32 v[132:133], v[16:17], v[32:33] op_sel_hi:[1,0]
	v_pk_mul_f32 v[94:95], v[16:17], v[124:125] op_sel_hi:[1,0]
	v_pk_fma_f32 v[132:133], v[12:13], v[32:33], v[132:133] op_sel:[0,1,0]
	v_pk_fma_f32 v[94:95], v[12:13], v[124:125], v[94:95] op_sel:[0,1,0]
	v_pk_fma_f32 v[132:133], v[18:19], v[34:35], v[132:133] op_sel_hi:[1,0,1]
	v_pk_fma_f32 v[94:95], v[18:19], v[126:127], v[94:95] op_sel_hi:[1,0,1]
	v_pk_fma_f32 v[132:133], v[14:15], v[34:35], v[132:133] op_sel:[0,1,0]
	v_pk_fma_f32 v[94:95], v[14:15], v[126:127], v[94:95] op_sel:[0,1,0]
	v_cvt_pk_f16_f32 v94, v94, v95
	v_add_f32_dpp v132, v132, v132 quad_perm:[1,0,3,2] row_mask:0xf bank_mask:0xf bound_ctrl:1
	v_add_f32_dpp v133, v133, v133 quad_perm:[1,0,3,2] row_mask:0xf bank_mask:0xf bound_ctrl:1
	ds_write2st64_b32 v93, v96, v94 offset0:0 offset1:4
	ds_read_b128 v[94:97], v42 offset:12800
	ds_read_b128 v[116:119], v42 offset:16896
	ds_read_b128 v[120:123], v42 offset:8704
	ds_read_b128 v[124:127], v42 offset:512
	ds_read_b64 v[130:131], v92 offset:256
	v_pk_fma_f32 v[16:17], v[28:29], v[90:91], v[16:17] op_sel_hi:[0,1,1]
	v_add_f32_dpp v132, v132, v132 quad_perm:[2,3,0,1] row_mask:0xf bank_mask:0xf bound_ctrl:1
	v_add_f32_dpp v133, v133, v133 quad_perm:[2,3,0,1] row_mask:0xf bank_mask:0xf bound_ctrl:1
	v_pk_fma_f32 v[12:13], v[28:29], v[90:91], v[12:13] op_sel:[1,0,0]
	v_add_f32_dpp v132, v132, v132 row_half_mirror row_mask:0xf bank_mask:0xf bound_ctrl:1
	v_add_f32_dpp v133, v133, v133 row_half_mirror row_mask:0xf bank_mask:0xf bound_ctrl:1
	v_pk_fma_f32 v[18:19], v[30:31], v[90:91], v[18:19] op_sel_hi:[0,1,1]
	v_pk_fma_f32 v[14:15], v[30:31], v[90:91], v[14:15] op_sel:[1,0,0]
	ds_read_b64 v[90:91], v115 offset:20992
	v_add_f32_dpp v132, v132, v132 row_mirror row_mask:0xf bank_mask:0xf bound_ctrl:1
	v_add_f32_dpp v133, v133, v133 row_mirror row_mask:0xf bank_mask:0xf bound_ctrl:1
	v_pk_fma_f32 v[16:17], v[24:25], v[132:133], v[16:17] op_sel_hi:[0,1,1]
	v_pk_fma_f32 v[12:13], v[24:25], v[132:133], v[12:13] op_sel:[1,0,0]
	v_pk_fma_f32 v[18:19], v[26:27], v[132:133], v[18:19] op_sel_hi:[0,1,1]
	v_pk_fma_f32 v[14:15], v[26:27], v[132:133], v[14:15] op_sel:[1,0,0]
	s_waitcnt lgkmcnt(1)
	v_pk_mul_f32 v[132:133], v[16:17], v[94:95] op_sel_hi:[1,0]
	v_pk_mul_f32 v[24:25], v[16:17], v[20:21] op_sel_hi:[1,0]
	v_pk_fma_f32 v[132:133], v[12:13], v[94:95], v[132:133] op_sel:[0,1,0]
	v_pk_fma_f32 v[24:25], v[12:13], v[20:21], v[24:25] op_sel:[0,1,0]
	v_pk_fma_f32 v[132:133], v[18:19], v[96:97], v[132:133] op_sel_hi:[1,0,1]
	v_pk_fma_f32 v[24:25], v[18:19], v[22:23], v[24:25] op_sel_hi:[1,0,1]
	v_pk_fma_f32 v[132:133], v[14:15], v[96:97], v[132:133] op_sel:[0,1,0]
	v_pk_fma_f32 v[24:25], v[14:15], v[22:23], v[24:25] op_sel:[0,1,0]
	v_cvt_pk_f16_f32 v96, v24, v25
	v_add_f32_dpp v132, v132, v132 quad_perm:[1,0,3,2] row_mask:0xf bank_mask:0xf bound_ctrl:1
	v_add_f32_dpp v133, v133, v133 quad_perm:[1,0,3,2] row_mask:0xf bank_mask:0xf bound_ctrl:1
	ds_read_b128 v[32:35], v114 offset:13312
	ds_read_b128 v[24:27], v114 offset:17408
	ds_read_b128 v[28:31], v114 offset:9216
	ds_read_b128 v[20:23], v114 offset:1024
	v_pk_fma_f32 v[16:17], v[120:121], v[130:131], v[16:17] op_sel_hi:[0,1,1]
	v_add_f32_dpp v132, v132, v132 quad_perm:[2,3,0,1] row_mask:0xf bank_mask:0xf bound_ctrl:1
	v_add_f32_dpp v133, v133, v133 quad_perm:[2,3,0,1] row_mask:0xf bank_mask:0xf bound_ctrl:1
	v_pk_fma_f32 v[12:13], v[120:121], v[130:131], v[12:13] op_sel:[1,0,0]
	v_add_f32_dpp v132, v132, v132 row_half_mirror row_mask:0xf bank_mask:0xf bound_ctrl:1
	v_add_f32_dpp v133, v133, v133 row_half_mirror row_mask:0xf bank_mask:0xf bound_ctrl:1
	v_pk_fma_f32 v[18:19], v[122:123], v[130:131], v[18:19] op_sel_hi:[0,1,1]
	v_pk_fma_f32 v[14:15], v[122:123], v[130:131], v[14:15] op_sel:[1,0,0]
	v_add_f32_dpp v132, v132, v132 row_mirror row_mask:0xf bank_mask:0xf bound_ctrl:1
	v_add_f32_dpp v133, v133, v133 row_mirror row_mask:0xf bank_mask:0xf bound_ctrl:1
	v_pk_fma_f32 v[16:17], v[116:117], v[132:133], v[16:17] op_sel_hi:[0,1,1]
	v_pk_fma_f32 v[12:13], v[116:117], v[132:133], v[12:13] op_sel:[1,0,0]
	v_pk_fma_f32 v[18:19], v[118:119], v[132:133], v[18:19] op_sel_hi:[0,1,1]
	v_pk_fma_f32 v[14:15], v[118:119], v[132:133], v[14:15] op_sel:[1,0,0]
	s_waitcnt lgkmcnt(0)
	v_pk_mul_f32 v[132:133], v[16:17], v[32:33] op_sel_hi:[1,0]
	v_pk_mul_f32 v[94:95], v[16:17], v[124:125] op_sel_hi:[1,0]
	v_pk_fma_f32 v[132:133], v[12:13], v[32:33], v[132:133] op_sel:[0,1,0]
	v_pk_fma_f32 v[94:95], v[12:13], v[124:125], v[94:95] op_sel:[0,1,0]
	v_pk_fma_f32 v[132:133], v[18:19], v[34:35], v[132:133] op_sel_hi:[1,0,1]
	v_pk_fma_f32 v[94:95], v[18:19], v[126:127], v[94:95] op_sel_hi:[1,0,1]
	v_pk_fma_f32 v[132:133], v[14:15], v[34:35], v[132:133] op_sel:[0,1,0]
	v_pk_fma_f32 v[94:95], v[14:15], v[126:127], v[94:95] op_sel:[0,1,0]
	v_cvt_pk_f16_f32 v94, v94, v95
	v_add_f32_dpp v132, v132, v132 quad_perm:[1,0,3,2] row_mask:0xf bank_mask:0xf bound_ctrl:1
	v_add_f32_dpp v133, v133, v133 quad_perm:[1,0,3,2] row_mask:0xf bank_mask:0xf bound_ctrl:1
	ds_write2st64_b32 v93, v96, v94 offset0:8 offset1:12
	ds_read_b128 v[94:97], v42 offset:13312
	ds_read_b128 v[116:119], v42 offset:17408
	ds_read_b128 v[120:123], v42 offset:9216
	ds_read_b128 v[124:127], v42 offset:1024
	ds_read_b64 v[130:131], v92 offset:512
	v_pk_fma_f32 v[16:17], v[28:29], v[90:91], v[16:17] op_sel_hi:[0,1,1]
	v_add_f32_dpp v132, v132, v132 quad_perm:[2,3,0,1] row_mask:0xf bank_mask:0xf bound_ctrl:1
	v_add_f32_dpp v133, v133, v133 quad_perm:[2,3,0,1] row_mask:0xf bank_mask:0xf bound_ctrl:1
	v_pk_fma_f32 v[12:13], v[28:29], v[90:91], v[12:13] op_sel:[1,0,0]
	v_add_f32_dpp v132, v132, v132 row_half_mirror row_mask:0xf bank_mask:0xf bound_ctrl:1
	v_add_f32_dpp v133, v133, v133 row_half_mirror row_mask:0xf bank_mask:0xf bound_ctrl:1
	v_pk_fma_f32 v[18:19], v[30:31], v[90:91], v[18:19] op_sel_hi:[0,1,1]
	v_pk_fma_f32 v[14:15], v[30:31], v[90:91], v[14:15] op_sel:[1,0,0]
	ds_read_b64 v[90:91], v115 offset:21248
	v_add_f32_dpp v132, v132, v132 row_mirror row_mask:0xf bank_mask:0xf bound_ctrl:1
	v_add_f32_dpp v133, v133, v133 row_mirror row_mask:0xf bank_mask:0xf bound_ctrl:1
	v_pk_fma_f32 v[16:17], v[24:25], v[132:133], v[16:17] op_sel_hi:[0,1,1]
	v_pk_fma_f32 v[12:13], v[24:25], v[132:133], v[12:13] op_sel:[1,0,0]
	v_pk_fma_f32 v[18:19], v[26:27], v[132:133], v[18:19] op_sel_hi:[0,1,1]
	v_pk_fma_f32 v[14:15], v[26:27], v[132:133], v[14:15] op_sel:[1,0,0]
	s_waitcnt lgkmcnt(1)
	v_pk_mul_f32 v[132:133], v[16:17], v[94:95] op_sel_hi:[1,0]
	v_pk_mul_f32 v[24:25], v[16:17], v[20:21] op_sel_hi:[1,0]
	v_pk_fma_f32 v[132:133], v[12:13], v[94:95], v[132:133] op_sel:[0,1,0]
	v_pk_fma_f32 v[24:25], v[12:13], v[20:21], v[24:25] op_sel:[0,1,0]
	v_pk_fma_f32 v[132:133], v[18:19], v[96:97], v[132:133] op_sel_hi:[1,0,1]
	v_pk_fma_f32 v[24:25], v[18:19], v[22:23], v[24:25] op_sel_hi:[1,0,1]
	v_pk_fma_f32 v[132:133], v[14:15], v[96:97], v[132:133] op_sel:[0,1,0]
	v_pk_fma_f32 v[24:25], v[14:15], v[22:23], v[24:25] op_sel:[0,1,0]
	v_cvt_pk_f16_f32 v96, v24, v25
	v_add_f32_dpp v132, v132, v132 quad_perm:[1,0,3,2] row_mask:0xf bank_mask:0xf bound_ctrl:1
	v_add_f32_dpp v133, v133, v133 quad_perm:[1,0,3,2] row_mask:0xf bank_mask:0xf bound_ctrl:1
	ds_read_b128 v[32:35], v114 offset:13824
	ds_read_b128 v[24:27], v114 offset:17920
	ds_read_b128 v[28:31], v114 offset:9728
	ds_read_b128 v[20:23], v114 offset:1536
	v_pk_fma_f32 v[16:17], v[120:121], v[130:131], v[16:17] op_sel_hi:[0,1,1]
	v_add_f32_dpp v132, v132, v132 quad_perm:[2,3,0,1] row_mask:0xf bank_mask:0xf bound_ctrl:1
	v_add_f32_dpp v133, v133, v133 quad_perm:[2,3,0,1] row_mask:0xf bank_mask:0xf bound_ctrl:1
	v_pk_fma_f32 v[12:13], v[120:121], v[130:131], v[12:13] op_sel:[1,0,0]
	v_add_f32_dpp v132, v132, v132 row_half_mirror row_mask:0xf bank_mask:0xf bound_ctrl:1
	v_add_f32_dpp v133, v133, v133 row_half_mirror row_mask:0xf bank_mask:0xf bound_ctrl:1
	v_pk_fma_f32 v[18:19], v[122:123], v[130:131], v[18:19] op_sel_hi:[0,1,1]
	v_pk_fma_f32 v[14:15], v[122:123], v[130:131], v[14:15] op_sel:[1,0,0]
	v_add_f32_dpp v132, v132, v132 row_mirror row_mask:0xf bank_mask:0xf bound_ctrl:1
	v_add_f32_dpp v133, v133, v133 row_mirror row_mask:0xf bank_mask:0xf bound_ctrl:1
	v_pk_fma_f32 v[16:17], v[116:117], v[132:133], v[16:17] op_sel_hi:[0,1,1]
	v_pk_fma_f32 v[12:13], v[116:117], v[132:133], v[12:13] op_sel:[1,0,0]
	v_pk_fma_f32 v[18:19], v[118:119], v[132:133], v[18:19] op_sel_hi:[0,1,1]
	v_pk_fma_f32 v[14:15], v[118:119], v[132:133], v[14:15] op_sel:[1,0,0]
	s_waitcnt lgkmcnt(0)
	v_pk_mul_f32 v[132:133], v[16:17], v[32:33] op_sel_hi:[1,0]
	v_pk_mul_f32 v[94:95], v[16:17], v[124:125] op_sel_hi:[1,0]
	v_pk_fma_f32 v[132:133], v[12:13], v[32:33], v[132:133] op_sel:[0,1,0]
	v_pk_fma_f32 v[94:95], v[12:13], v[124:125], v[94:95] op_sel:[0,1,0]
	v_pk_fma_f32 v[132:133], v[18:19], v[34:35], v[132:133] op_sel_hi:[1,0,1]
	v_pk_fma_f32 v[94:95], v[18:19], v[126:127], v[94:95] op_sel_hi:[1,0,1]
	v_pk_fma_f32 v[132:133], v[14:15], v[34:35], v[132:133] op_sel:[0,1,0]
	v_pk_fma_f32 v[94:95], v[14:15], v[126:127], v[94:95] op_sel:[0,1,0]
	v_cvt_pk_f16_f32 v94, v94, v95
	v_add_f32_dpp v132, v132, v132 quad_perm:[1,0,3,2] row_mask:0xf bank_mask:0xf bound_ctrl:1
	v_add_f32_dpp v133, v133, v133 quad_perm:[1,0,3,2] row_mask:0xf bank_mask:0xf bound_ctrl:1
	ds_write2st64_b32 v93, v96, v94 offset0:16 offset1:20
	ds_read_b128 v[94:97], v42 offset:13824
	ds_read_b128 v[116:119], v42 offset:17920
	ds_read_b128 v[120:123], v42 offset:9728
	ds_read_b128 v[124:127], v42 offset:1536
	ds_read_b64 v[130:131], v92 offset:768
	v_pk_fma_f32 v[16:17], v[28:29], v[90:91], v[16:17] op_sel_hi:[0,1,1]
	v_add_f32_dpp v132, v132, v132 quad_perm:[2,3,0,1] row_mask:0xf bank_mask:0xf bound_ctrl:1
	v_add_f32_dpp v133, v133, v133 quad_perm:[2,3,0,1] row_mask:0xf bank_mask:0xf bound_ctrl:1
	v_pk_fma_f32 v[12:13], v[28:29], v[90:91], v[12:13] op_sel:[1,0,0]
	v_add_f32_dpp v132, v132, v132 row_half_mirror row_mask:0xf bank_mask:0xf bound_ctrl:1
	v_add_f32_dpp v133, v133, v133 row_half_mirror row_mask:0xf bank_mask:0xf bound_ctrl:1
	v_pk_fma_f32 v[18:19], v[30:31], v[90:91], v[18:19] op_sel_hi:[0,1,1]
	v_pk_fma_f32 v[14:15], v[30:31], v[90:91], v[14:15] op_sel:[1,0,0]
	ds_read_b64 v[90:91], v115 offset:21504
	v_add_f32_dpp v132, v132, v132 row_mirror row_mask:0xf bank_mask:0xf bound_ctrl:1
	v_add_f32_dpp v133, v133, v133 row_mirror row_mask:0xf bank_mask:0xf bound_ctrl:1
	v_pk_fma_f32 v[16:17], v[24:25], v[132:133], v[16:17] op_sel_hi:[0,1,1]
	v_pk_fma_f32 v[12:13], v[24:25], v[132:133], v[12:13] op_sel:[1,0,0]
	v_pk_fma_f32 v[18:19], v[26:27], v[132:133], v[18:19] op_sel_hi:[0,1,1]
	v_pk_fma_f32 v[14:15], v[26:27], v[132:133], v[14:15] op_sel:[1,0,0]
	s_waitcnt lgkmcnt(1)
	v_pk_mul_f32 v[132:133], v[16:17], v[94:95] op_sel_hi:[1,0]
	v_pk_mul_f32 v[24:25], v[16:17], v[20:21] op_sel_hi:[1,0]
	v_pk_fma_f32 v[132:133], v[12:13], v[94:95], v[132:133] op_sel:[0,1,0]
	v_pk_fma_f32 v[24:25], v[12:13], v[20:21], v[24:25] op_sel:[0,1,0]
	v_pk_fma_f32 v[132:133], v[18:19], v[96:97], v[132:133] op_sel_hi:[1,0,1]
	v_pk_fma_f32 v[24:25], v[18:19], v[22:23], v[24:25] op_sel_hi:[1,0,1]
	v_pk_fma_f32 v[132:133], v[14:15], v[96:97], v[132:133] op_sel:[0,1,0]
	v_pk_fma_f32 v[24:25], v[14:15], v[22:23], v[24:25] op_sel:[0,1,0]
	v_cvt_pk_f16_f32 v96, v24, v25
	v_add_f32_dpp v132, v132, v132 quad_perm:[1,0,3,2] row_mask:0xf bank_mask:0xf bound_ctrl:1
	v_add_f32_dpp v133, v133, v133 quad_perm:[1,0,3,2] row_mask:0xf bank_mask:0xf bound_ctrl:1
	ds_read_b128 v[32:35], v114 offset:14336
	ds_read_b128 v[24:27], v114 offset:18432
	ds_read_b128 v[28:31], v114 offset:10240
	ds_read_b128 v[20:23], v114 offset:2048
	v_pk_fma_f32 v[16:17], v[120:121], v[130:131], v[16:17] op_sel_hi:[0,1,1]
	v_add_f32_dpp v132, v132, v132 quad_perm:[2,3,0,1] row_mask:0xf bank_mask:0xf bound_ctrl:1
	v_add_f32_dpp v133, v133, v133 quad_perm:[2,3,0,1] row_mask:0xf bank_mask:0xf bound_ctrl:1
	v_pk_fma_f32 v[12:13], v[120:121], v[130:131], v[12:13] op_sel:[1,0,0]
	v_add_f32_dpp v132, v132, v132 row_half_mirror row_mask:0xf bank_mask:0xf bound_ctrl:1
	v_add_f32_dpp v133, v133, v133 row_half_mirror row_mask:0xf bank_mask:0xf bound_ctrl:1
	v_pk_fma_f32 v[18:19], v[122:123], v[130:131], v[18:19] op_sel_hi:[0,1,1]
	v_pk_fma_f32 v[14:15], v[122:123], v[130:131], v[14:15] op_sel:[1,0,0]
	v_add_f32_dpp v132, v132, v132 row_mirror row_mask:0xf bank_mask:0xf bound_ctrl:1
	v_add_f32_dpp v133, v133, v133 row_mirror row_mask:0xf bank_mask:0xf bound_ctrl:1
	v_pk_fma_f32 v[16:17], v[116:117], v[132:133], v[16:17] op_sel_hi:[0,1,1]
	v_pk_fma_f32 v[12:13], v[116:117], v[132:133], v[12:13] op_sel:[1,0,0]
	v_pk_fma_f32 v[18:19], v[118:119], v[132:133], v[18:19] op_sel_hi:[0,1,1]
	v_pk_fma_f32 v[14:15], v[118:119], v[132:133], v[14:15] op_sel:[1,0,0]
	s_waitcnt lgkmcnt(0)
	v_pk_mul_f32 v[132:133], v[16:17], v[32:33] op_sel_hi:[1,0]
	v_pk_mul_f32 v[94:95], v[16:17], v[124:125] op_sel_hi:[1,0]
	v_pk_fma_f32 v[132:133], v[12:13], v[32:33], v[132:133] op_sel:[0,1,0]
	v_pk_fma_f32 v[94:95], v[12:13], v[124:125], v[94:95] op_sel:[0,1,0]
	v_pk_fma_f32 v[132:133], v[18:19], v[34:35], v[132:133] op_sel_hi:[1,0,1]
	v_pk_fma_f32 v[94:95], v[18:19], v[126:127], v[94:95] op_sel_hi:[1,0,1]
	v_pk_fma_f32 v[132:133], v[14:15], v[34:35], v[132:133] op_sel:[0,1,0]
	v_pk_fma_f32 v[94:95], v[14:15], v[126:127], v[94:95] op_sel:[0,1,0]
	v_cvt_pk_f16_f32 v94, v94, v95
	v_add_f32_dpp v132, v132, v132 quad_perm:[1,0,3,2] row_mask:0xf bank_mask:0xf bound_ctrl:1
	v_add_f32_dpp v133, v133, v133 quad_perm:[1,0,3,2] row_mask:0xf bank_mask:0xf bound_ctrl:1
	ds_write2st64_b32 v93, v96, v94 offset0:24 offset1:28
	ds_read_b128 v[94:97], v42 offset:14336
	ds_read_b128 v[116:119], v42 offset:18432
	ds_read_b128 v[120:123], v42 offset:10240
	ds_read_b128 v[124:127], v42 offset:2048
	ds_read_b64 v[130:131], v92 offset:1024
	v_pk_fma_f32 v[16:17], v[28:29], v[90:91], v[16:17] op_sel_hi:[0,1,1]
	v_add_f32_dpp v132, v132, v132 quad_perm:[2,3,0,1] row_mask:0xf bank_mask:0xf bound_ctrl:1
	v_add_f32_dpp v133, v133, v133 quad_perm:[2,3,0,1] row_mask:0xf bank_mask:0xf bound_ctrl:1
	v_pk_fma_f32 v[12:13], v[28:29], v[90:91], v[12:13] op_sel:[1,0,0]
	v_add_f32_dpp v132, v132, v132 row_half_mirror row_mask:0xf bank_mask:0xf bound_ctrl:1
	v_add_f32_dpp v133, v133, v133 row_half_mirror row_mask:0xf bank_mask:0xf bound_ctrl:1
	v_pk_fma_f32 v[18:19], v[30:31], v[90:91], v[18:19] op_sel_hi:[0,1,1]
	v_pk_fma_f32 v[14:15], v[30:31], v[90:91], v[14:15] op_sel:[1,0,0]
	ds_read_b64 v[90:91], v115 offset:21760
	v_add_f32_dpp v132, v132, v132 row_mirror row_mask:0xf bank_mask:0xf bound_ctrl:1
	v_add_f32_dpp v133, v133, v133 row_mirror row_mask:0xf bank_mask:0xf bound_ctrl:1
	v_pk_fma_f32 v[16:17], v[24:25], v[132:133], v[16:17] op_sel_hi:[0,1,1]
	v_pk_fma_f32 v[12:13], v[24:25], v[132:133], v[12:13] op_sel:[1,0,0]
	v_pk_fma_f32 v[18:19], v[26:27], v[132:133], v[18:19] op_sel_hi:[0,1,1]
	v_pk_fma_f32 v[14:15], v[26:27], v[132:133], v[14:15] op_sel:[1,0,0]
	s_waitcnt lgkmcnt(1)
	v_pk_mul_f32 v[132:133], v[16:17], v[94:95] op_sel_hi:[1,0]
	v_pk_mul_f32 v[24:25], v[16:17], v[20:21] op_sel_hi:[1,0]
	v_pk_fma_f32 v[132:133], v[12:13], v[94:95], v[132:133] op_sel:[0,1,0]
	v_pk_fma_f32 v[24:25], v[12:13], v[20:21], v[24:25] op_sel:[0,1,0]
	v_pk_fma_f32 v[132:133], v[18:19], v[96:97], v[132:133] op_sel_hi:[1,0,1]
	v_pk_fma_f32 v[24:25], v[18:19], v[22:23], v[24:25] op_sel_hi:[1,0,1]
	v_pk_fma_f32 v[132:133], v[14:15], v[96:97], v[132:133] op_sel:[0,1,0]
	v_pk_fma_f32 v[24:25], v[14:15], v[22:23], v[24:25] op_sel:[0,1,0]
	v_cvt_pk_f16_f32 v96, v24, v25
	v_add_f32_dpp v132, v132, v132 quad_perm:[1,0,3,2] row_mask:0xf bank_mask:0xf bound_ctrl:1
	v_add_f32_dpp v133, v133, v133 quad_perm:[1,0,3,2] row_mask:0xf bank_mask:0xf bound_ctrl:1
	ds_read_b128 v[32:35], v114 offset:14848
	ds_read_b128 v[24:27], v114 offset:18944
	ds_read_b128 v[28:31], v114 offset:10752
	ds_read_b128 v[20:23], v114 offset:2560
	v_pk_fma_f32 v[16:17], v[120:121], v[130:131], v[16:17] op_sel_hi:[0,1,1]
	v_add_f32_dpp v132, v132, v132 quad_perm:[2,3,0,1] row_mask:0xf bank_mask:0xf bound_ctrl:1
	v_add_f32_dpp v133, v133, v133 quad_perm:[2,3,0,1] row_mask:0xf bank_mask:0xf bound_ctrl:1
	v_pk_fma_f32 v[12:13], v[120:121], v[130:131], v[12:13] op_sel:[1,0,0]
	v_add_f32_dpp v132, v132, v132 row_half_mirror row_mask:0xf bank_mask:0xf bound_ctrl:1
	v_add_f32_dpp v133, v133, v133 row_half_mirror row_mask:0xf bank_mask:0xf bound_ctrl:1
	v_pk_fma_f32 v[18:19], v[122:123], v[130:131], v[18:19] op_sel_hi:[0,1,1]
	v_pk_fma_f32 v[14:15], v[122:123], v[130:131], v[14:15] op_sel:[1,0,0]
	v_add_f32_dpp v132, v132, v132 row_mirror row_mask:0xf bank_mask:0xf bound_ctrl:1
	v_add_f32_dpp v133, v133, v133 row_mirror row_mask:0xf bank_mask:0xf bound_ctrl:1
	v_pk_fma_f32 v[16:17], v[116:117], v[132:133], v[16:17] op_sel_hi:[0,1,1]
	v_pk_fma_f32 v[12:13], v[116:117], v[132:133], v[12:13] op_sel:[1,0,0]
	v_pk_fma_f32 v[18:19], v[118:119], v[132:133], v[18:19] op_sel_hi:[0,1,1]
	v_pk_fma_f32 v[14:15], v[118:119], v[132:133], v[14:15] op_sel:[1,0,0]
	s_waitcnt lgkmcnt(0)
	v_pk_mul_f32 v[132:133], v[16:17], v[32:33] op_sel_hi:[1,0]
	v_pk_mul_f32 v[94:95], v[16:17], v[124:125] op_sel_hi:[1,0]
	v_pk_fma_f32 v[132:133], v[12:13], v[32:33], v[132:133] op_sel:[0,1,0]
	v_pk_fma_f32 v[94:95], v[12:13], v[124:125], v[94:95] op_sel:[0,1,0]
	v_pk_fma_f32 v[132:133], v[18:19], v[34:35], v[132:133] op_sel_hi:[1,0,1]
	v_pk_fma_f32 v[94:95], v[18:19], v[126:127], v[94:95] op_sel_hi:[1,0,1]
	v_pk_fma_f32 v[132:133], v[14:15], v[34:35], v[132:133] op_sel:[0,1,0]
	v_pk_fma_f32 v[94:95], v[14:15], v[126:127], v[94:95] op_sel:[0,1,0]
	v_cvt_pk_f16_f32 v94, v94, v95
	v_add_f32_dpp v132, v132, v132 quad_perm:[1,0,3,2] row_mask:0xf bank_mask:0xf bound_ctrl:1
	v_add_f32_dpp v133, v133, v133 quad_perm:[1,0,3,2] row_mask:0xf bank_mask:0xf bound_ctrl:1
	ds_write2st64_b32 v93, v96, v94 offset0:32 offset1:36
	ds_read_b128 v[94:97], v42 offset:14848
	ds_read_b128 v[116:119], v42 offset:18944
	ds_read_b128 v[120:123], v42 offset:10752
	ds_read_b128 v[124:127], v42 offset:2560
	ds_read_b64 v[130:131], v92 offset:1280
	v_pk_fma_f32 v[16:17], v[28:29], v[90:91], v[16:17] op_sel_hi:[0,1,1]
	v_add_f32_dpp v132, v132, v132 quad_perm:[2,3,0,1] row_mask:0xf bank_mask:0xf bound_ctrl:1
	v_add_f32_dpp v133, v133, v133 quad_perm:[2,3,0,1] row_mask:0xf bank_mask:0xf bound_ctrl:1
	v_pk_fma_f32 v[12:13], v[28:29], v[90:91], v[12:13] op_sel:[1,0,0]
	v_add_f32_dpp v132, v132, v132 row_half_mirror row_mask:0xf bank_mask:0xf bound_ctrl:1
	v_add_f32_dpp v133, v133, v133 row_half_mirror row_mask:0xf bank_mask:0xf bound_ctrl:1
	v_pk_fma_f32 v[18:19], v[30:31], v[90:91], v[18:19] op_sel_hi:[0,1,1]
	v_pk_fma_f32 v[14:15], v[30:31], v[90:91], v[14:15] op_sel:[1,0,0]
	ds_read_b64 v[90:91], v115 offset:22016
	v_add_f32_dpp v132, v132, v132 row_mirror row_mask:0xf bank_mask:0xf bound_ctrl:1
	v_add_f32_dpp v133, v133, v133 row_mirror row_mask:0xf bank_mask:0xf bound_ctrl:1
	v_pk_fma_f32 v[16:17], v[24:25], v[132:133], v[16:17] op_sel_hi:[0,1,1]
	v_pk_fma_f32 v[12:13], v[24:25], v[132:133], v[12:13] op_sel:[1,0,0]
	v_pk_fma_f32 v[18:19], v[26:27], v[132:133], v[18:19] op_sel_hi:[0,1,1]
	v_pk_fma_f32 v[14:15], v[26:27], v[132:133], v[14:15] op_sel:[1,0,0]
	s_waitcnt lgkmcnt(1)
	v_pk_mul_f32 v[132:133], v[16:17], v[94:95] op_sel_hi:[1,0]
	v_pk_mul_f32 v[24:25], v[16:17], v[20:21] op_sel_hi:[1,0]
	v_pk_fma_f32 v[132:133], v[12:13], v[94:95], v[132:133] op_sel:[0,1,0]
	v_pk_fma_f32 v[24:25], v[12:13], v[20:21], v[24:25] op_sel:[0,1,0]
	v_pk_fma_f32 v[132:133], v[18:19], v[96:97], v[132:133] op_sel_hi:[1,0,1]
	v_pk_fma_f32 v[24:25], v[18:19], v[22:23], v[24:25] op_sel_hi:[1,0,1]
	v_pk_fma_f32 v[132:133], v[14:15], v[96:97], v[132:133] op_sel:[0,1,0]
	v_pk_fma_f32 v[24:25], v[14:15], v[22:23], v[24:25] op_sel:[0,1,0]
	v_cvt_pk_f16_f32 v96, v24, v25
	v_add_f32_dpp v132, v132, v132 quad_perm:[1,0,3,2] row_mask:0xf bank_mask:0xf bound_ctrl:1
	v_add_f32_dpp v133, v133, v133 quad_perm:[1,0,3,2] row_mask:0xf bank_mask:0xf bound_ctrl:1
	ds_read_b128 v[32:35], v114 offset:15360
	ds_read_b128 v[24:27], v114 offset:19456
	ds_read_b128 v[28:31], v114 offset:11264
	ds_read_b128 v[20:23], v114 offset:3072
	v_pk_fma_f32 v[16:17], v[120:121], v[130:131], v[16:17] op_sel_hi:[0,1,1]
	v_add_f32_dpp v132, v132, v132 quad_perm:[2,3,0,1] row_mask:0xf bank_mask:0xf bound_ctrl:1
	v_add_f32_dpp v133, v133, v133 quad_perm:[2,3,0,1] row_mask:0xf bank_mask:0xf bound_ctrl:1
	v_pk_fma_f32 v[12:13], v[120:121], v[130:131], v[12:13] op_sel:[1,0,0]
	v_add_f32_dpp v132, v132, v132 row_half_mirror row_mask:0xf bank_mask:0xf bound_ctrl:1
	v_add_f32_dpp v133, v133, v133 row_half_mirror row_mask:0xf bank_mask:0xf bound_ctrl:1
	v_pk_fma_f32 v[18:19], v[122:123], v[130:131], v[18:19] op_sel_hi:[0,1,1]
	v_pk_fma_f32 v[14:15], v[122:123], v[130:131], v[14:15] op_sel:[1,0,0]
	v_add_f32_dpp v132, v132, v132 row_mirror row_mask:0xf bank_mask:0xf bound_ctrl:1
	v_add_f32_dpp v133, v133, v133 row_mirror row_mask:0xf bank_mask:0xf bound_ctrl:1
	v_pk_fma_f32 v[16:17], v[116:117], v[132:133], v[16:17] op_sel_hi:[0,1,1]
	v_pk_fma_f32 v[12:13], v[116:117], v[132:133], v[12:13] op_sel:[1,0,0]
	v_pk_fma_f32 v[18:19], v[118:119], v[132:133], v[18:19] op_sel_hi:[0,1,1]
	v_pk_fma_f32 v[14:15], v[118:119], v[132:133], v[14:15] op_sel:[1,0,0]
	s_waitcnt lgkmcnt(0)
	v_pk_mul_f32 v[132:133], v[16:17], v[32:33] op_sel_hi:[1,0]
	v_pk_mul_f32 v[94:95], v[16:17], v[124:125] op_sel_hi:[1,0]
	v_pk_fma_f32 v[132:133], v[12:13], v[32:33], v[132:133] op_sel:[0,1,0]
	v_pk_fma_f32 v[94:95], v[12:13], v[124:125], v[94:95] op_sel:[0,1,0]
	v_pk_fma_f32 v[132:133], v[18:19], v[34:35], v[132:133] op_sel_hi:[1,0,1]
	v_pk_fma_f32 v[94:95], v[18:19], v[126:127], v[94:95] op_sel_hi:[1,0,1]
	v_pk_fma_f32 v[132:133], v[14:15], v[34:35], v[132:133] op_sel:[0,1,0]
	v_pk_fma_f32 v[94:95], v[14:15], v[126:127], v[94:95] op_sel:[0,1,0]
	v_cvt_pk_f16_f32 v94, v94, v95
	v_add_f32_dpp v132, v132, v132 quad_perm:[1,0,3,2] row_mask:0xf bank_mask:0xf bound_ctrl:1
	v_add_f32_dpp v133, v133, v133 quad_perm:[1,0,3,2] row_mask:0xf bank_mask:0xf bound_ctrl:1
	ds_write2st64_b32 v93, v96, v94 offset0:40 offset1:44
	ds_read_b128 v[94:97], v42 offset:15360
	ds_read_b128 v[116:119], v42 offset:19456
	ds_read_b128 v[120:123], v42 offset:11264
	ds_read_b128 v[124:127], v42 offset:3072
	ds_read_b64 v[130:131], v92 offset:1536
	v_pk_fma_f32 v[16:17], v[28:29], v[90:91], v[16:17] op_sel_hi:[0,1,1]
	v_add_f32_dpp v132, v132, v132 quad_perm:[2,3,0,1] row_mask:0xf bank_mask:0xf bound_ctrl:1
	v_add_f32_dpp v133, v133, v133 quad_perm:[2,3,0,1] row_mask:0xf bank_mask:0xf bound_ctrl:1
	v_pk_fma_f32 v[12:13], v[28:29], v[90:91], v[12:13] op_sel:[1,0,0]
	v_add_f32_dpp v132, v132, v132 row_half_mirror row_mask:0xf bank_mask:0xf bound_ctrl:1
	v_add_f32_dpp v133, v133, v133 row_half_mirror row_mask:0xf bank_mask:0xf bound_ctrl:1
	v_pk_fma_f32 v[18:19], v[30:31], v[90:91], v[18:19] op_sel_hi:[0,1,1]
	v_pk_fma_f32 v[14:15], v[30:31], v[90:91], v[14:15] op_sel:[1,0,0]
	ds_read_b64 v[90:91], v115 offset:22272
	v_add_f32_dpp v132, v132, v132 row_mirror row_mask:0xf bank_mask:0xf bound_ctrl:1
	v_add_f32_dpp v133, v133, v133 row_mirror row_mask:0xf bank_mask:0xf bound_ctrl:1
	v_pk_fma_f32 v[16:17], v[24:25], v[132:133], v[16:17] op_sel_hi:[0,1,1]
	v_pk_fma_f32 v[12:13], v[24:25], v[132:133], v[12:13] op_sel:[1,0,0]
	v_pk_fma_f32 v[18:19], v[26:27], v[132:133], v[18:19] op_sel_hi:[0,1,1]
	v_pk_fma_f32 v[14:15], v[26:27], v[132:133], v[14:15] op_sel:[1,0,0]
	s_waitcnt lgkmcnt(1)
	v_pk_mul_f32 v[132:133], v[16:17], v[94:95] op_sel_hi:[1,0]
	v_pk_mul_f32 v[24:25], v[16:17], v[20:21] op_sel_hi:[1,0]
	v_pk_fma_f32 v[132:133], v[12:13], v[94:95], v[132:133] op_sel:[0,1,0]
	v_pk_fma_f32 v[24:25], v[12:13], v[20:21], v[24:25] op_sel:[0,1,0]
	v_pk_fma_f32 v[132:133], v[18:19], v[96:97], v[132:133] op_sel_hi:[1,0,1]
	v_pk_fma_f32 v[24:25], v[18:19], v[22:23], v[24:25] op_sel_hi:[1,0,1]
	v_pk_fma_f32 v[132:133], v[14:15], v[96:97], v[132:133] op_sel:[0,1,0]
	v_pk_fma_f32 v[24:25], v[14:15], v[22:23], v[24:25] op_sel:[0,1,0]
	v_cvt_pk_f16_f32 v96, v24, v25
	v_add_f32_dpp v132, v132, v132 quad_perm:[1,0,3,2] row_mask:0xf bank_mask:0xf bound_ctrl:1
	v_add_f32_dpp v133, v133, v133 quad_perm:[1,0,3,2] row_mask:0xf bank_mask:0xf bound_ctrl:1
	ds_read_b128 v[32:35], v114 offset:15872
	ds_read_b128 v[24:27], v114 offset:19968
	ds_read_b128 v[28:31], v114 offset:11776
	ds_read_b128 v[20:23], v114 offset:3584
	v_pk_fma_f32 v[16:17], v[120:121], v[130:131], v[16:17] op_sel_hi:[0,1,1]
	v_add_f32_dpp v132, v132, v132 quad_perm:[2,3,0,1] row_mask:0xf bank_mask:0xf bound_ctrl:1
	v_add_f32_dpp v133, v133, v133 quad_perm:[2,3,0,1] row_mask:0xf bank_mask:0xf bound_ctrl:1
	v_pk_fma_f32 v[12:13], v[120:121], v[130:131], v[12:13] op_sel:[1,0,0]
	v_add_f32_dpp v132, v132, v132 row_half_mirror row_mask:0xf bank_mask:0xf bound_ctrl:1
	v_add_f32_dpp v133, v133, v133 row_half_mirror row_mask:0xf bank_mask:0xf bound_ctrl:1
	v_pk_fma_f32 v[18:19], v[122:123], v[130:131], v[18:19] op_sel_hi:[0,1,1]
	v_pk_fma_f32 v[14:15], v[122:123], v[130:131], v[14:15] op_sel:[1,0,0]
	v_add_f32_dpp v132, v132, v132 row_mirror row_mask:0xf bank_mask:0xf bound_ctrl:1
	v_add_f32_dpp v133, v133, v133 row_mirror row_mask:0xf bank_mask:0xf bound_ctrl:1
	v_pk_fma_f32 v[16:17], v[116:117], v[132:133], v[16:17] op_sel_hi:[0,1,1]
	v_pk_fma_f32 v[12:13], v[116:117], v[132:133], v[12:13] op_sel:[1,0,0]
	v_pk_fma_f32 v[18:19], v[118:119], v[132:133], v[18:19] op_sel_hi:[0,1,1]
	v_pk_fma_f32 v[14:15], v[118:119], v[132:133], v[14:15] op_sel:[1,0,0]
	s_waitcnt lgkmcnt(0)
	v_pk_mul_f32 v[132:133], v[16:17], v[32:33] op_sel_hi:[1,0]
	v_pk_mul_f32 v[94:95], v[16:17], v[124:125] op_sel_hi:[1,0]
	v_pk_fma_f32 v[132:133], v[12:13], v[32:33], v[132:133] op_sel:[0,1,0]
	v_pk_fma_f32 v[94:95], v[12:13], v[124:125], v[94:95] op_sel:[0,1,0]
	v_pk_fma_f32 v[132:133], v[18:19], v[34:35], v[132:133] op_sel_hi:[1,0,1]
	v_pk_fma_f32 v[94:95], v[18:19], v[126:127], v[94:95] op_sel_hi:[1,0,1]
	v_pk_fma_f32 v[132:133], v[14:15], v[34:35], v[132:133] op_sel:[0,1,0]
	v_pk_fma_f32 v[94:95], v[14:15], v[126:127], v[94:95] op_sel:[0,1,0]
	v_cvt_pk_f16_f32 v94, v94, v95
	v_add_f32_dpp v132, v132, v132 quad_perm:[1,0,3,2] row_mask:0xf bank_mask:0xf bound_ctrl:1
	v_add_f32_dpp v133, v133, v133 quad_perm:[1,0,3,2] row_mask:0xf bank_mask:0xf bound_ctrl:1
	ds_write2st64_b32 v93, v96, v94 offset0:48 offset1:52
	ds_read_b128 v[94:97], v42 offset:15872
	ds_read_b128 v[116:119], v42 offset:19968
	ds_read_b128 v[120:123], v42 offset:11776
	ds_read_b128 v[124:127], v42 offset:3584
	ds_read_b64 v[130:131], v92 offset:1792
	v_pk_fma_f32 v[16:17], v[28:29], v[90:91], v[16:17] op_sel_hi:[0,1,1]
	v_add_f32_dpp v132, v132, v132 quad_perm:[2,3,0,1] row_mask:0xf bank_mask:0xf bound_ctrl:1
	v_add_f32_dpp v133, v133, v133 quad_perm:[2,3,0,1] row_mask:0xf bank_mask:0xf bound_ctrl:1
	v_pk_fma_f32 v[12:13], v[28:29], v[90:91], v[12:13] op_sel:[1,0,0]
	v_add_f32_dpp v132, v132, v132 row_half_mirror row_mask:0xf bank_mask:0xf bound_ctrl:1
	v_add_f32_dpp v133, v133, v133 row_half_mirror row_mask:0xf bank_mask:0xf bound_ctrl:1
	v_pk_fma_f32 v[18:19], v[30:31], v[90:91], v[18:19] op_sel_hi:[0,1,1]
	v_pk_fma_f32 v[14:15], v[30:31], v[90:91], v[14:15] op_sel:[1,0,0]
	ds_read_b64 v[90:91], v115 offset:22272
	v_add_f32_dpp v132, v132, v132 row_mirror row_mask:0xf bank_mask:0xf bound_ctrl:1
	v_add_f32_dpp v133, v133, v133 row_mirror row_mask:0xf bank_mask:0xf bound_ctrl:1
	v_pk_fma_f32 v[16:17], v[24:25], v[132:133], v[16:17] op_sel_hi:[0,1,1]
	v_pk_fma_f32 v[12:13], v[24:25], v[132:133], v[12:13] op_sel:[1,0,0]
	v_pk_fma_f32 v[18:19], v[26:27], v[132:133], v[18:19] op_sel_hi:[0,1,1]
	v_pk_fma_f32 v[14:15], v[26:27], v[132:133], v[14:15] op_sel:[1,0,0]
	s_waitcnt lgkmcnt(1)
	v_pk_mul_f32 v[132:133], v[16:17], v[94:95] op_sel_hi:[1,0]
	v_pk_mul_f32 v[24:25], v[16:17], v[20:21] op_sel_hi:[1,0]
	v_pk_fma_f32 v[132:133], v[12:13], v[94:95], v[132:133] op_sel:[0,1,0]
	v_pk_fma_f32 v[24:25], v[12:13], v[20:21], v[24:25] op_sel:[0,1,0]
	v_pk_fma_f32 v[132:133], v[18:19], v[96:97], v[132:133] op_sel_hi:[1,0,1]
	v_pk_fma_f32 v[24:25], v[18:19], v[22:23], v[24:25] op_sel_hi:[1,0,1]
	v_pk_fma_f32 v[132:133], v[14:15], v[96:97], v[132:133] op_sel:[0,1,0]
	v_pk_fma_f32 v[24:25], v[14:15], v[22:23], v[24:25] op_sel:[0,1,0]
	v_cvt_pk_f16_f32 v96, v24, v25
	v_add_f32_dpp v132, v132, v132 quad_perm:[1,0,3,2] row_mask:0xf bank_mask:0xf bound_ctrl:1
	v_add_f32_dpp v133, v133, v133 quad_perm:[1,0,3,2] row_mask:0xf bank_mask:0xf bound_ctrl:1
	ds_read_b128 v[32:35], v114 offset:15872
	ds_read_b128 v[24:27], v114 offset:19968
	ds_read_b128 v[28:31], v114 offset:11776
	ds_read_b128 v[20:23], v114 offset:3584
	v_pk_fma_f32 v[16:17], v[120:121], v[130:131], v[16:17] op_sel_hi:[0,1,1]
	v_add_f32_dpp v132, v132, v132 quad_perm:[2,3,0,1] row_mask:0xf bank_mask:0xf bound_ctrl:1
	v_add_f32_dpp v133, v133, v133 quad_perm:[2,3,0,1] row_mask:0xf bank_mask:0xf bound_ctrl:1
	v_pk_fma_f32 v[12:13], v[120:121], v[130:131], v[12:13] op_sel:[1,0,0]
	v_add_f32_dpp v132, v132, v132 row_half_mirror row_mask:0xf bank_mask:0xf bound_ctrl:1
	v_add_f32_dpp v133, v133, v133 row_half_mirror row_mask:0xf bank_mask:0xf bound_ctrl:1
	v_pk_fma_f32 v[18:19], v[122:123], v[130:131], v[18:19] op_sel_hi:[0,1,1]
	v_pk_fma_f32 v[14:15], v[122:123], v[130:131], v[14:15] op_sel:[1,0,0]
	v_add_f32_dpp v132, v132, v132 row_mirror row_mask:0xf bank_mask:0xf bound_ctrl:1
	v_add_f32_dpp v133, v133, v133 row_mirror row_mask:0xf bank_mask:0xf bound_ctrl:1
	v_pk_fma_f32 v[16:17], v[116:117], v[132:133], v[16:17] op_sel_hi:[0,1,1]
	v_pk_fma_f32 v[12:13], v[116:117], v[132:133], v[12:13] op_sel:[1,0,0]
	v_pk_fma_f32 v[18:19], v[118:119], v[132:133], v[18:19] op_sel_hi:[0,1,1]
	v_pk_fma_f32 v[14:15], v[118:119], v[132:133], v[14:15] op_sel:[1,0,0]
	v_pk_mul_f32 v[94:95], v[16:17], v[124:125] op_sel_hi:[1,0]
	v_pk_fma_f32 v[94:95], v[12:13], v[124:125], v[94:95] op_sel:[0,1,0]
	v_pk_fma_f32 v[94:95], v[18:19], v[126:127], v[94:95] op_sel_hi:[1,0,1]
	v_pk_fma_f32 v[94:95], v[14:15], v[126:127], v[94:95] op_sel:[0,1,0]
	v_cvt_pk_f16_f32 v94, v94, v95
	ds_write2st64_b32 v93, v96, v94 offset0:56 offset1:60
	v_swap_b32 v17, v12
	v_swap_b32 v19, v14
	s_waitcnt vmcnt(10) lgkmcnt(1)
	v_cvt_f32_f16_sdwa v91, v60 dst_sel:DWORD dst_unused:UNUSED_PAD src0_sel:WORD_1
	v_cvt_f32_f16_e32 v90, v60
	v_cvt_f32_f16_sdwa v93, v61 dst_sel:DWORD dst_unused:UNUSED_PAD src0_sel:WORD_1
	v_cvt_f32_f16_e32 v92, v61
	s_waitcnt vmcnt(7)
	v_cvt_f32_f16_sdwa v25, v68 dst_sel:DWORD dst_unused:UNUSED_PAD src0_sel:WORD_1
	v_cvt_f32_f16_e32 v24, v68
	v_cvt_f32_f16_sdwa v27, v69 dst_sel:DWORD dst_unused:UNUSED_PAD src0_sel:WORD_1
	v_cvt_f32_f16_e32 v26, v69
	v_pk_mul_f32 v[30:31], v[0:1], v[90:91]
	v_pk_mul_f32 v[28:29], v[2:3], v[92:93]
	v_pk_mul_f32 v[96:97], v[30:31], v[30:31]
	v_pk_mul_f32 v[94:95], v[28:29], v[28:29]
	v_add_f32_e32 v42, v96, v97
	v_cvt_f32_f16_sdwa v33, v58 dst_sel:DWORD dst_unused:UNUSED_PAD src0_sel:WORD_1
	v_cvt_f32_f16_e32 v32, v58
	v_cvt_f32_f16_sdwa v35, v59 dst_sel:DWORD dst_unused:UNUSED_PAD src0_sel:WORD_1
	v_cvt_f32_f16_e32 v34, v59
	v_add_f32_e32 v42, v94, v42
	v_add_f32_e32 v42, v95, v42
	v_pk_add_f32 v[94:95], v[24:25], -1.0 op_sel_hi:[1,0]
	v_pk_add_f32 v[96:97], v[26:27], -1.0 op_sel_hi:[1,0]
	v_pk_fma_f32 v[94:95], v[4:5], v[94:95], 1.0 op_sel_hi:[1,1,0]
	v_pk_fma_f32 v[96:97], v[6:7], v[96:97], 1.0 op_sel_hi:[1,1,0]
	v_pk_mul_f32 v[94:95], v[90:91], v[94:95]
	v_pk_mul_f32 v[96:97], v[92:93], v[96:97]
	v_pk_mul_f32 v[90:91], v[32:33], v[94:95]
	v_pk_mul_f32 v[92:93], v[34:35], v[96:97]
	v_pk_mul_f32 v[90:91], v[8:9], v[90:91]
	v_pk_mul_f32 v[92:93], v[10:11], v[92:93]
	v_add_f32_e32 v90, v90, v91
	v_add_f32_e32 v91, v92, v93
	ds_read_b128 v[20:23], v114 offset:7936
	v_add_f32_e32 v90, v90, v91
	v_add_f32_dpp v42, v42, v42 quad_perm:[1,0,3,2] row_mask:0xf bank_mask:0xf bound_ctrl:1
	s_nop 0
	v_add_f32_dpp v90, v90, v90 quad_perm:[1,0,3,2] row_mask:0xf bank_mask:0xf bound_ctrl:1
	v_add_f32_dpp v42, v42, v42 quad_perm:[2,3,0,1] row_mask:0xf bank_mask:0xf bound_ctrl:1
	s_nop 0
	v_add_f32_dpp v90, v90, v90 quad_perm:[2,3,0,1] row_mask:0xf bank_mask:0xf bound_ctrl:1
	v_add_f32_dpp v42, v42, v42 row_half_mirror row_mask:0xf bank_mask:0xf bound_ctrl:1
	s_nop 0
	v_add_f32_dpp v90, v90, v90 row_half_mirror row_mask:0xf bank_mask:0xf bound_ctrl:1
	v_mov_b32_dpp v116, v42 row_mirror row_mask:0xf bank_mask:0xf bound_ctrl:1
	s_nop 0
	v_mov_b32_dpp v91, v90 row_mirror row_mask:0xf bank_mask:0xf bound_ctrl:1
	s_and_saveexec_b64 s[12:13], s[6:7]
	s_cbranch_execz .LBB0_419
	s_add_i32 s50, s94, 16
	v_cmp_lt_u32_e32 vcc, s50, v106
	s_and_b64 exec, exec, vcc
	s_cbranch_execz .LBB0_419
	v_add_f32_e32 v92, v90, v91
	v_add_u32_e32 v90, s50, v46
	v_ashrrev_i32_e32 v91, 31, v90
	v_lshlrev_b64 v[90:91], 6, v[90:91]
	v_lshl_add_u64 v[90:91], s[58:59], 0, v[90:91]
	global_store_dword v[90:91], v92, off

.LBB0_426:
	v_swap_b32 v29, v34
	v_swap_b32 v33, v90
	s_waitcnt lgkmcnt(0)
	v_pk_mul_f32 v[134:135], v[28:29], v[24:25] op_sel_hi:[1,0]
	v_pk_fma_f32 v[134:135], v[34:35], v[24:25], v[134:135] op_sel:[0,1,0]
	v_pk_fma_f32 v[134:135], v[32:33], v[26:27], v[134:135] op_sel_hi:[1,0,1]
	v_pk_fma_f32 v[134:135], v[90:91], v[26:27], v[134:135] op_sel:[0,1,0]
	ds_read_b128 v[116:119], v93 offset:12288
	ds_read_b128 v[120:123], v93 offset:16384
	ds_read_b128 v[124:127], v93 offset:8192
	ds_read_b128 v[130:133], v93
	ds_read_b64 v[96:97], v92
	v_pk_fma_f32 v[28:29], v[20:21], v[30:31], v[28:29] op_sel_hi:[0,1,1]
	v_pk_fma_f32 v[34:35], v[20:21], v[30:31], v[34:35] op_sel:[1,0,0]
	v_add_f32_dpp v134, v134, v134 quad_perm:[1,0,3,2] row_mask:0xf bank_mask:0xf bound_ctrl:1
	v_add_f32_dpp v135, v135, v135 quad_perm:[1,0,3,2] row_mask:0xf bank_mask:0xf bound_ctrl:1
	v_pk_fma_f32 v[32:33], v[22:23], v[30:31], v[32:33] op_sel_hi:[0,1,1]
	v_add_f32_dpp v134, v134, v134 quad_perm:[2,3,0,1] row_mask:0xf bank_mask:0xf bound_ctrl:1
	v_add_f32_dpp v135, v135, v135 quad_perm:[2,3,0,1] row_mask:0xf bank_mask:0xf bound_ctrl:1
	v_pk_fma_f32 v[90:91], v[22:23], v[30:31], v[90:91] op_sel:[1,0,0]
	v_add_f32_dpp v134, v134, v134 row_half_mirror row_mask:0xf bank_mask:0xf bound_ctrl:1
	v_add_f32_dpp v135, v135, v135 row_half_mirror row_mask:0xf bank_mask:0xf bound_ctrl:1
	ds_read_b64 v[30:31], v95 offset:20736
	v_add_f32_dpp v134, v134, v134 row_mirror row_mask:0xf bank_mask:0xf bound_ctrl:1
	v_add_f32_dpp v135, v135, v135 row_mirror row_mask:0xf bank_mask:0xf bound_ctrl:1
	v_pk_fma_f32 v[28:29], v[16:17], v[134:135], v[28:29] op_sel_hi:[0,1,1]
	v_pk_fma_f32 v[34:35], v[16:17], v[134:135], v[34:35] op_sel:[1,0,0]
	v_pk_fma_f32 v[32:33], v[18:19], v[134:135], v[32:33] op_sel_hi:[0,1,1]
	v_pk_fma_f32 v[90:91], v[18:19], v[134:135], v[90:91] op_sel:[1,0,0]
	s_waitcnt lgkmcnt(1)
	v_pk_mul_f32 v[134:135], v[28:29], v[116:117] op_sel_hi:[1,0]
	v_pk_mul_f32 v[16:17], v[28:29], v[12:13] op_sel_hi:[1,0]
	v_pk_fma_f32 v[134:135], v[34:35], v[116:117], v[134:135] op_sel:[0,1,0]
	v_pk_fma_f32 v[16:17], v[34:35], v[12:13], v[16:17] op_sel:[0,1,0]
	v_pk_fma_f32 v[134:135], v[32:33], v[118:119], v[134:135] op_sel_hi:[1,0,1]
	v_pk_fma_f32 v[16:17], v[32:33], v[14:15], v[16:17] op_sel_hi:[1,0,1]
	v_pk_fma_f32 v[134:135], v[90:91], v[118:119], v[134:135] op_sel:[0,1,0]
	v_pk_fma_f32 v[16:17], v[90:91], v[14:15], v[16:17] op_sel:[0,1,0]
	v_cvt_pk_f16_f32 v118, v16, v17
	v_add_f32_dpp v134, v134, v134 quad_perm:[1,0,3,2] row_mask:0xf bank_mask:0xf bound_ctrl:1
	v_add_f32_dpp v135, v135, v135 quad_perm:[1,0,3,2] row_mask:0xf bank_mask:0xf bound_ctrl:1
	ds_read_b128 v[24:27], v94 offset:12800
	ds_read_b128 v[16:19], v94 offset:16896
	ds_read_b128 v[20:23], v94 offset:8704
	ds_read_b128 v[12:15], v94 offset:512
	v_pk_fma_f32 v[28:29], v[124:125], v[96:97], v[28:29] op_sel_hi:[0,1,1]
	v_add_f32_dpp v134, v134, v134 quad_perm:[2,3,0,1] row_mask:0xf bank_mask:0xf bound_ctrl:1
	v_add_f32_dpp v135, v135, v135 quad_perm:[2,3,0,1] row_mask:0xf bank_mask:0xf bound_ctrl:1
	v_pk_fma_f32 v[34:35], v[124:125], v[96:97], v[34:35] op_sel:[1,0,0]
	v_add_f32_dpp v134, v134, v134 row_half_mirror row_mask:0xf bank_mask:0xf bound_ctrl:1
	v_add_f32_dpp v135, v135, v135 row_half_mirror row_mask:0xf bank_mask:0xf bound_ctrl:1
	v_pk_fma_f32 v[32:33], v[126:127], v[96:97], v[32:33] op_sel_hi:[0,1,1]
	v_pk_fma_f32 v[90:91], v[126:127], v[96:97], v[90:91] op_sel:[1,0,0]
	v_add_f32_dpp v134, v134, v134 row_mirror row_mask:0xf bank_mask:0xf bound_ctrl:1
	v_add_f32_dpp v135, v135, v135 row_mirror row_mask:0xf bank_mask:0xf bound_ctrl:1
	v_pk_fma_f32 v[28:29], v[120:121], v[134:135], v[28:29] op_sel_hi:[0,1,1]
	v_pk_fma_f32 v[34:35], v[120:121], v[134:135], v[34:35] op_sel:[1,0,0]
	v_pk_fma_f32 v[32:33], v[122:123], v[134:135], v[32:33] op_sel_hi:[0,1,1]
	v_pk_fma_f32 v[90:91], v[122:123], v[134:135], v[90:91] op_sel:[1,0,0]
	s_waitcnt lgkmcnt(0)
	v_pk_mul_f32 v[134:135], v[28:29], v[24:25] op_sel_hi:[1,0]
	v_pk_mul_f32 v[116:117], v[28:29], v[130:131] op_sel_hi:[1,0]
	v_pk_fma_f32 v[134:135], v[34:35], v[24:25], v[134:135] op_sel:[0,1,0]
	v_pk_fma_f32 v[116:117], v[34:35], v[130:131], v[116:117] op_sel:[0,1,0]
	v_pk_fma_f32 v[134:135], v[32:33], v[26:27], v[134:135] op_sel_hi:[1,0,1]
	v_pk_fma_f32 v[116:117], v[32:33], v[132:133], v[116:117] op_sel_hi:[1,0,1]
	v_pk_fma_f32 v[134:135], v[90:91], v[26:27], v[134:135] op_sel:[0,1,0]
	v_pk_fma_f32 v[116:117], v[90:91], v[132:133], v[116:117] op_sel:[0,1,0]
	v_cvt_pk_f16_f32 v116, v116, v117
	v_add_f32_dpp v134, v134, v134 quad_perm:[1,0,3,2] row_mask:0xf bank_mask:0xf bound_ctrl:1
	v_add_f32_dpp v135, v135, v135 quad_perm:[1,0,3,2] row_mask:0xf bank_mask:0xf bound_ctrl:1
	ds_write2st64_b32 v42, v118, v116 offset0:0 offset1:4
	ds_read_b128 v[116:119], v93 offset:12800
	ds_read_b128 v[120:123], v93 offset:16896
	ds_read_b128 v[124:127], v93 offset:8704
	ds_read_b128 v[130:133], v93 offset:512
	ds_read_b64 v[96:97], v92 offset:256
	v_pk_fma_f32 v[28:29], v[20:21], v[30:31], v[28:29] op_sel_hi:[0,1,1]
	v_add_f32_dpp v134, v134, v134 quad_perm:[2,3,0,1] row_mask:0xf bank_mask:0xf bound_ctrl:1
	v_add_f32_dpp v135, v135, v135 quad_perm:[2,3,0,1] row_mask:0xf bank_mask:0xf bound_ctrl:1
	v_pk_fma_f32 v[34:35], v[20:21], v[30:31], v[34:35] op_sel:[1,0,0]
	v_add_f32_dpp v134, v134, v134 row_half_mirror row_mask:0xf bank_mask:0xf bound_ctrl:1
	v_add_f32_dpp v135, v135, v135 row_half_mirror row_mask:0xf bank_mask:0xf bound_ctrl:1
	v_pk_fma_f32 v[32:33], v[22:23], v[30:31], v[32:33] op_sel_hi:[0,1,1]
	v_pk_fma_f32 v[90:91], v[22:23], v[30:31], v[90:91] op_sel:[1,0,0]
	ds_read_b64 v[30:31], v95 offset:20992
	v_add_f32_dpp v134, v134, v134 row_mirror row_mask:0xf bank_mask:0xf bound_ctrl:1
	v_add_f32_dpp v135, v135, v135 row_mirror row_mask:0xf bank_mask:0xf bound_ctrl:1
	v_pk_fma_f32 v[28:29], v[16:17], v[134:135], v[28:29] op_sel_hi:[0,1,1]
	v_pk_fma_f32 v[34:35], v[16:17], v[134:135], v[34:35] op_sel:[1,0,0]
	v_pk_fma_f32 v[32:33], v[18:19], v[134:135], v[32:33] op_sel_hi:[0,1,1]
	v_pk_fma_f32 v[90:91], v[18:19], v[134:135], v[90:91] op_sel:[1,0,0]
	s_waitcnt lgkmcnt(1)
	v_pk_mul_f32 v[134:135], v[28:29], v[116:117] op_sel_hi:[1,0]
	v_pk_mul_f32 v[16:17], v[28:29], v[12:13] op_sel_hi:[1,0]
	v_pk_fma_f32 v[134:135], v[34:35], v[116:117], v[134:135] op_sel:[0,1,0]
	v_pk_fma_f32 v[16:17], v[34:35], v[12:13], v[16:17] op_sel:[0,1,0]
	v_pk_fma_f32 v[134:135], v[32:33], v[118:119], v[134:135] op_sel_hi:[1,0,1]
	v_pk_fma_f32 v[16:17], v[32:33], v[14:15], v[16:17] op_sel_hi:[1,0,1]
	v_pk_fma_f32 v[134:135], v[90:91], v[118:119], v[134:135] op_sel:[0,1,0]
	v_pk_fma_f32 v[16:17], v[90:91], v[14:15], v[16:17] op_sel:[0,1,0]
	v_cvt_pk_f16_f32 v118, v16, v17
	v_add_f32_dpp v134, v134, v134 quad_perm:[1,0,3,2] row_mask:0xf bank_mask:0xf bound_ctrl:1
	v_add_f32_dpp v135, v135, v135 quad_perm:[1,0,3,2] row_mask:0xf bank_mask:0xf bound_ctrl:1
	ds_read_b128 v[24:27], v94 offset:13312
	ds_read_b128 v[16:19], v94 offset:17408
	ds_read_b128 v[20:23], v94 offset:9216
	ds_read_b128 v[12:15], v94 offset:1024
	v_pk_fma_f32 v[28:29], v[124:125], v[96:97], v[28:29] op_sel_hi:[0,1,1]
	v_add_f32_dpp v134, v134, v134 quad_perm:[2,3,0,1] row_mask:0xf bank_mask:0xf bound_ctrl:1
	v_add_f32_dpp v135, v135, v135 quad_perm:[2,3,0,1] row_mask:0xf bank_mask:0xf bound_ctrl:1
	v_pk_fma_f32 v[34:35], v[124:125], v[96:97], v[34:35] op_sel:[1,0,0]
	v_add_f32_dpp v134, v134, v134 row_half_mirror row_mask:0xf bank_mask:0xf bound_ctrl:1
	v_add_f32_dpp v135, v135, v135 row_half_mirror row_mask:0xf bank_mask:0xf bound_ctrl:1
	v_pk_fma_f32 v[32:33], v[126:127], v[96:97], v[32:33] op_sel_hi:[0,1,1]
	v_pk_fma_f32 v[90:91], v[126:127], v[96:97], v[90:91] op_sel:[1,0,0]
	v_add_f32_dpp v134, v134, v134 row_mirror row_mask:0xf bank_mask:0xf bound_ctrl:1
	v_add_f32_dpp v135, v135, v135 row_mirror row_mask:0xf bank_mask:0xf bound_ctrl:1
	v_pk_fma_f32 v[28:29], v[120:121], v[134:135], v[28:29] op_sel_hi:[0,1,1]
	v_pk_fma_f32 v[34:35], v[120:121], v[134:135], v[34:35] op_sel:[1,0,0]
	v_pk_fma_f32 v[32:33], v[122:123], v[134:135], v[32:33] op_sel_hi:[0,1,1]
	v_pk_fma_f32 v[90:91], v[122:123], v[134:135], v[90:91] op_sel:[1,0,0]
	s_waitcnt lgkmcnt(0)
	v_pk_mul_f32 v[134:135], v[28:29], v[24:25] op_sel_hi:[1,0]
	v_pk_mul_f32 v[116:117], v[28:29], v[130:131] op_sel_hi:[1,0]
	v_pk_fma_f32 v[134:135], v[34:35], v[24:25], v[134:135] op_sel:[0,1,0]
	v_pk_fma_f32 v[116:117], v[34:35], v[130:131], v[116:117] op_sel:[0,1,0]
	v_pk_fma_f32 v[134:135], v[32:33], v[26:27], v[134:135] op_sel_hi:[1,0,1]
	v_pk_fma_f32 v[116:117], v[32:33], v[132:133], v[116:117] op_sel_hi:[1,0,1]
	v_pk_fma_f32 v[134:135], v[90:91], v[26:27], v[134:135] op_sel:[0,1,0]
	v_pk_fma_f32 v[116:117], v[90:91], v[132:133], v[116:117] op_sel:[0,1,0]
	v_cvt_pk_f16_f32 v116, v116, v117
	v_add_f32_dpp v134, v134, v134 quad_perm:[1,0,3,2] row_mask:0xf bank_mask:0xf bound_ctrl:1
	v_add_f32_dpp v135, v135, v135 quad_perm:[1,0,3,2] row_mask:0xf bank_mask:0xf bound_ctrl:1
	ds_write2st64_b32 v42, v118, v116 offset0:8 offset1:12
	ds_read_b128 v[116:119], v93 offset:13312
	ds_read_b128 v[120:123], v93 offset:17408
	ds_read_b128 v[124:127], v93 offset:9216
	ds_read_b128 v[130:133], v93 offset:1024
	ds_read_b64 v[96:97], v92 offset:512
	v_pk_fma_f32 v[28:29], v[20:21], v[30:31], v[28:29] op_sel_hi:[0,1,1]
	v_add_f32_dpp v134, v134, v134 quad_perm:[2,3,0,1] row_mask:0xf bank_mask:0xf bound_ctrl:1
	v_add_f32_dpp v135, v135, v135 quad_perm:[2,3,0,1] row_mask:0xf bank_mask:0xf bound_ctrl:1
	v_pk_fma_f32 v[34:35], v[20:21], v[30:31], v[34:35] op_sel:[1,0,0]
	v_add_f32_dpp v134, v134, v134 row_half_mirror row_mask:0xf bank_mask:0xf bound_ctrl:1
	v_add_f32_dpp v135, v135, v135 row_half_mirror row_mask:0xf bank_mask:0xf bound_ctrl:1
	v_pk_fma_f32 v[32:33], v[22:23], v[30:31], v[32:33] op_sel_hi:[0,1,1]
	v_pk_fma_f32 v[90:91], v[22:23], v[30:31], v[90:91] op_sel:[1,0,0]
	ds_read_b64 v[30:31], v95 offset:21248
	v_add_f32_dpp v134, v134, v134 row_mirror row_mask:0xf bank_mask:0xf bound_ctrl:1
	v_add_f32_dpp v135, v135, v135 row_mirror row_mask:0xf bank_mask:0xf bound_ctrl:1
	v_pk_fma_f32 v[28:29], v[16:17], v[134:135], v[28:29] op_sel_hi:[0,1,1]
	v_pk_fma_f32 v[34:35], v[16:17], v[134:135], v[34:35] op_sel:[1,0,0]
	v_pk_fma_f32 v[32:33], v[18:19], v[134:135], v[32:33] op_sel_hi:[0,1,1]
	v_pk_fma_f32 v[90:91], v[18:19], v[134:135], v[90:91] op_sel:[1,0,0]
	s_waitcnt lgkmcnt(1)
	v_pk_mul_f32 v[134:135], v[28:29], v[116:117] op_sel_hi:[1,0]
	v_pk_mul_f32 v[16:17], v[28:29], v[12:13] op_sel_hi:[1,0]
	v_pk_fma_f32 v[134:135], v[34:35], v[116:117], v[134:135] op_sel:[0,1,0]
	v_pk_fma_f32 v[16:17], v[34:35], v[12:13], v[16:17] op_sel:[0,1,0]
	v_pk_fma_f32 v[134:135], v[32:33], v[118:119], v[134:135] op_sel_hi:[1,0,1]
	v_pk_fma_f32 v[16:17], v[32:33], v[14:15], v[16:17] op_sel_hi:[1,0,1]
	v_pk_fma_f32 v[134:135], v[90:91], v[118:119], v[134:135] op_sel:[0,1,0]
	v_pk_fma_f32 v[16:17], v[90:91], v[14:15], v[16:17] op_sel:[0,1,0]
	v_cvt_pk_f16_f32 v118, v16, v17
	v_add_f32_dpp v134, v134, v134 quad_perm:[1,0,3,2] row_mask:0xf bank_mask:0xf bound_ctrl:1
	v_add_f32_dpp v135, v135, v135 quad_perm:[1,0,3,2] row_mask:0xf bank_mask:0xf bound_ctrl:1
	ds_read_b128 v[24:27], v94 offset:13824
	ds_read_b128 v[16:19], v94 offset:17920
	ds_read_b128 v[20:23], v94 offset:9728
	ds_read_b128 v[12:15], v94 offset:1536
	v_pk_fma_f32 v[28:29], v[124:125], v[96:97], v[28:29] op_sel_hi:[0,1,1]
	v_add_f32_dpp v134, v134, v134 quad_perm:[2,3,0,1] row_mask:0xf bank_mask:0xf bound_ctrl:1
	v_add_f32_dpp v135, v135, v135 quad_perm:[2,3,0,1] row_mask:0xf bank_mask:0xf bound_ctrl:1
	v_pk_fma_f32 v[34:35], v[124:125], v[96:97], v[34:35] op_sel:[1,0,0]
	v_add_f32_dpp v134, v134, v134 row_half_mirror row_mask:0xf bank_mask:0xf bound_ctrl:1
	v_add_f32_dpp v135, v135, v135 row_half_mirror row_mask:0xf bank_mask:0xf bound_ctrl:1
	v_pk_fma_f32 v[32:33], v[126:127], v[96:97], v[32:33] op_sel_hi:[0,1,1]
	v_pk_fma_f32 v[90:91], v[126:127], v[96:97], v[90:91] op_sel:[1,0,0]
	v_add_f32_dpp v134, v134, v134 row_mirror row_mask:0xf bank_mask:0xf bound_ctrl:1
	v_add_f32_dpp v135, v135, v135 row_mirror row_mask:0xf bank_mask:0xf bound_ctrl:1
	v_pk_fma_f32 v[28:29], v[120:121], v[134:135], v[28:29] op_sel_hi:[0,1,1]
	v_pk_fma_f32 v[34:35], v[120:121], v[134:135], v[34:35] op_sel:[1,0,0]
	v_pk_fma_f32 v[32:33], v[122:123], v[134:135], v[32:33] op_sel_hi:[0,1,1]
	v_pk_fma_f32 v[90:91], v[122:123], v[134:135], v[90:91] op_sel:[1,0,0]
	s_waitcnt lgkmcnt(0)
	v_pk_mul_f32 v[134:135], v[28:29], v[24:25] op_sel_hi:[1,0]
	v_pk_mul_f32 v[116:117], v[28:29], v[130:131] op_sel_hi:[1,0]
	v_pk_fma_f32 v[134:135], v[34:35], v[24:25], v[134:135] op_sel:[0,1,0]
	v_pk_fma_f32 v[116:117], v[34:35], v[130:131], v[116:117] op_sel:[0,1,0]
	v_pk_fma_f32 v[134:135], v[32:33], v[26:27], v[134:135] op_sel_hi:[1,0,1]
	v_pk_fma_f32 v[116:117], v[32:33], v[132:133], v[116:117] op_sel_hi:[1,0,1]
	v_pk_fma_f32 v[134:135], v[90:91], v[26:27], v[134:135] op_sel:[0,1,0]
	v_pk_fma_f32 v[116:117], v[90:91], v[132:133], v[116:117] op_sel:[0,1,0]
	v_cvt_pk_f16_f32 v116, v116, v117
	v_add_f32_dpp v134, v134, v134 quad_perm:[1,0,3,2] row_mask:0xf bank_mask:0xf bound_ctrl:1
	v_add_f32_dpp v135, v135, v135 quad_perm:[1,0,3,2] row_mask:0xf bank_mask:0xf bound_ctrl:1
	ds_write2st64_b32 v42, v118, v116 offset0:16 offset1:20
	ds_read_b128 v[116:119], v93 offset:13824
	ds_read_b128 v[120:123], v93 offset:17920
	ds_read_b128 v[124:127], v93 offset:9728
	ds_read_b128 v[130:133], v93 offset:1536
	ds_read_b64 v[96:97], v92 offset:768
	v_pk_fma_f32 v[28:29], v[20:21], v[30:31], v[28:29] op_sel_hi:[0,1,1]
	v_add_f32_dpp v134, v134, v134 quad_perm:[2,3,0,1] row_mask:0xf bank_mask:0xf bound_ctrl:1
	v_add_f32_dpp v135, v135, v135 quad_perm:[2,3,0,1] row_mask:0xf bank_mask:0xf bound_ctrl:1
	v_pk_fma_f32 v[34:35], v[20:21], v[30:31], v[34:35] op_sel:[1,0,0]
	v_add_f32_dpp v134, v134, v134 row_half_mirror row_mask:0xf bank_mask:0xf bound_ctrl:1
	v_add_f32_dpp v135, v135, v135 row_half_mirror row_mask:0xf bank_mask:0xf bound_ctrl:1
	v_pk_fma_f32 v[32:33], v[22:23], v[30:31], v[32:33] op_sel_hi:[0,1,1]
	v_pk_fma_f32 v[90:91], v[22:23], v[30:31], v[90:91] op_sel:[1,0,0]
	ds_read_b64 v[30:31], v95 offset:21504
	v_add_f32_dpp v134, v134, v134 row_mirror row_mask:0xf bank_mask:0xf bound_ctrl:1
	v_add_f32_dpp v135, v135, v135 row_mirror row_mask:0xf bank_mask:0xf bound_ctrl:1
	v_pk_fma_f32 v[28:29], v[16:17], v[134:135], v[28:29] op_sel_hi:[0,1,1]
	v_pk_fma_f32 v[34:35], v[16:17], v[134:135], v[34:35] op_sel:[1,0,0]
	v_pk_fma_f32 v[32:33], v[18:19], v[134:135], v[32:33] op_sel_hi:[0,1,1]
	v_pk_fma_f32 v[90:91], v[18:19], v[134:135], v[90:91] op_sel:[1,0,0]
	s_waitcnt lgkmcnt(1)
	v_pk_mul_f32 v[134:135], v[28:29], v[116:117] op_sel_hi:[1,0]
	v_pk_mul_f32 v[16:17], v[28:29], v[12:13] op_sel_hi:[1,0]
	v_pk_fma_f32 v[134:135], v[34:35], v[116:117], v[134:135] op_sel:[0,1,0]
	v_pk_fma_f32 v[16:17], v[34:35], v[12:13], v[16:17] op_sel:[0,1,0]
	v_pk_fma_f32 v[134:135], v[32:33], v[118:119], v[134:135] op_sel_hi:[1,0,1]
	v_pk_fma_f32 v[16:17], v[32:33], v[14:15], v[16:17] op_sel_hi:[1,0,1]
	v_pk_fma_f32 v[134:135], v[90:91], v[118:119], v[134:135] op_sel:[0,1,0]
	v_pk_fma_f32 v[16:17], v[90:91], v[14:15], v[16:17] op_sel:[0,1,0]
	v_cvt_pk_f16_f32 v118, v16, v17
	v_add_f32_dpp v134, v134, v134 quad_perm:[1,0,3,2] row_mask:0xf bank_mask:0xf bound_ctrl:1
	v_add_f32_dpp v135, v135, v135 quad_perm:[1,0,3,2] row_mask:0xf bank_mask:0xf bound_ctrl:1
	ds_read_b128 v[24:27], v94 offset:14336
	ds_read_b128 v[16:19], v94 offset:18432
	ds_read_b128 v[20:23], v94 offset:10240
	ds_read_b128 v[12:15], v94 offset:2048
	v_pk_fma_f32 v[28:29], v[124:125], v[96:97], v[28:29] op_sel_hi:[0,1,1]
	v_add_f32_dpp v134, v134, v134 quad_perm:[2,3,0,1] row_mask:0xf bank_mask:0xf bound_ctrl:1
	v_add_f32_dpp v135, v135, v135 quad_perm:[2,3,0,1] row_mask:0xf bank_mask:0xf bound_ctrl:1
	v_pk_fma_f32 v[34:35], v[124:125], v[96:97], v[34:35] op_sel:[1,0,0]
	v_add_f32_dpp v134, v134, v134 row_half_mirror row_mask:0xf bank_mask:0xf bound_ctrl:1
	v_add_f32_dpp v135, v135, v135 row_half_mirror row_mask:0xf bank_mask:0xf bound_ctrl:1
	v_pk_fma_f32 v[32:33], v[126:127], v[96:97], v[32:33] op_sel_hi:[0,1,1]
	v_pk_fma_f32 v[90:91], v[126:127], v[96:97], v[90:91] op_sel:[1,0,0]
	v_add_f32_dpp v134, v134, v134 row_mirror row_mask:0xf bank_mask:0xf bound_ctrl:1
	v_add_f32_dpp v135, v135, v135 row_mirror row_mask:0xf bank_mask:0xf bound_ctrl:1
	v_pk_fma_f32 v[28:29], v[120:121], v[134:135], v[28:29] op_sel_hi:[0,1,1]
	v_pk_fma_f32 v[34:35], v[120:121], v[134:135], v[34:35] op_sel:[1,0,0]
	v_pk_fma_f32 v[32:33], v[122:123], v[134:135], v[32:33] op_sel_hi:[0,1,1]
	v_pk_fma_f32 v[90:91], v[122:123], v[134:135], v[90:91] op_sel:[1,0,0]
	s_waitcnt lgkmcnt(0)
	v_pk_mul_f32 v[134:135], v[28:29], v[24:25] op_sel_hi:[1,0]
	v_pk_mul_f32 v[116:117], v[28:29], v[130:131] op_sel_hi:[1,0]
	v_pk_fma_f32 v[134:135], v[34:35], v[24:25], v[134:135] op_sel:[0,1,0]
	v_pk_fma_f32 v[116:117], v[34:35], v[130:131], v[116:117] op_sel:[0,1,0]
	v_pk_fma_f32 v[134:135], v[32:33], v[26:27], v[134:135] op_sel_hi:[1,0,1]
	v_pk_fma_f32 v[116:117], v[32:33], v[132:133], v[116:117] op_sel_hi:[1,0,1]
	v_pk_fma_f32 v[134:135], v[90:91], v[26:27], v[134:135] op_sel:[0,1,0]
	v_pk_fma_f32 v[116:117], v[90:91], v[132:133], v[116:117] op_sel:[0,1,0]
	v_cvt_pk_f16_f32 v116, v116, v117
	v_add_f32_dpp v134, v134, v134 quad_perm:[1,0,3,2] row_mask:0xf bank_mask:0xf bound_ctrl:1
	v_add_f32_dpp v135, v135, v135 quad_perm:[1,0,3,2] row_mask:0xf bank_mask:0xf bound_ctrl:1
	ds_write2st64_b32 v42, v118, v116 offset0:24 offset1:28
	ds_read_b128 v[116:119], v93 offset:14336
	ds_read_b128 v[120:123], v93 offset:18432
	ds_read_b128 v[124:127], v93 offset:10240
	ds_read_b128 v[130:133], v93 offset:2048
	ds_read_b64 v[96:97], v92 offset:1024
	v_pk_fma_f32 v[28:29], v[20:21], v[30:31], v[28:29] op_sel_hi:[0,1,1]
	v_add_f32_dpp v134, v134, v134 quad_perm:[2,3,0,1] row_mask:0xf bank_mask:0xf bound_ctrl:1
	v_add_f32_dpp v135, v135, v135 quad_perm:[2,3,0,1] row_mask:0xf bank_mask:0xf bound_ctrl:1
	v_pk_fma_f32 v[34:35], v[20:21], v[30:31], v[34:35] op_sel:[1,0,0]
	v_add_f32_dpp v134, v134, v134 row_half_mirror row_mask:0xf bank_mask:0xf bound_ctrl:1
	v_add_f32_dpp v135, v135, v135 row_half_mirror row_mask:0xf bank_mask:0xf bound_ctrl:1
	v_pk_fma_f32 v[32:33], v[22:23], v[30:31], v[32:33] op_sel_hi:[0,1,1]
	v_pk_fma_f32 v[90:91], v[22:23], v[30:31], v[90:91] op_sel:[1,0,0]
	ds_read_b64 v[30:31], v95 offset:21760
	v_add_f32_dpp v134, v134, v134 row_mirror row_mask:0xf bank_mask:0xf bound_ctrl:1
	v_add_f32_dpp v135, v135, v135 row_mirror row_mask:0xf bank_mask:0xf bound_ctrl:1
	v_pk_fma_f32 v[28:29], v[16:17], v[134:135], v[28:29] op_sel_hi:[0,1,1]
	v_pk_fma_f32 v[34:35], v[16:17], v[134:135], v[34:35] op_sel:[1,0,0]
	v_pk_fma_f32 v[32:33], v[18:19], v[134:135], v[32:33] op_sel_hi:[0,1,1]
	v_pk_fma_f32 v[90:91], v[18:19], v[134:135], v[90:91] op_sel:[1,0,0]
	s_waitcnt lgkmcnt(1)
	v_pk_mul_f32 v[134:135], v[28:29], v[116:117] op_sel_hi:[1,0]
	v_pk_mul_f32 v[16:17], v[28:29], v[12:13] op_sel_hi:[1,0]
	v_pk_fma_f32 v[134:135], v[34:35], v[116:117], v[134:135] op_sel:[0,1,0]
	v_pk_fma_f32 v[16:17], v[34:35], v[12:13], v[16:17] op_sel:[0,1,0]
	v_pk_fma_f32 v[134:135], v[32:33], v[118:119], v[134:135] op_sel_hi:[1,0,1]
	v_pk_fma_f32 v[16:17], v[32:33], v[14:15], v[16:17] op_sel_hi:[1,0,1]
	v_pk_fma_f32 v[134:135], v[90:91], v[118:119], v[134:135] op_sel:[0,1,0]
	v_pk_fma_f32 v[16:17], v[90:91], v[14:15], v[16:17] op_sel:[0,1,0]
	v_cvt_pk_f16_f32 v118, v16, v17
	v_add_f32_dpp v134, v134, v134 quad_perm:[1,0,3,2] row_mask:0xf bank_mask:0xf bound_ctrl:1
	v_add_f32_dpp v135, v135, v135 quad_perm:[1,0,3,2] row_mask:0xf bank_mask:0xf bound_ctrl:1
	ds_read_b128 v[24:27], v94 offset:14848
	ds_read_b128 v[16:19], v94 offset:18944
	ds_read_b128 v[20:23], v94 offset:10752
	ds_read_b128 v[12:15], v94 offset:2560
	v_pk_fma_f32 v[28:29], v[124:125], v[96:97], v[28:29] op_sel_hi:[0,1,1]
	v_add_f32_dpp v134, v134, v134 quad_perm:[2,3,0,1] row_mask:0xf bank_mask:0xf bound_ctrl:1
	v_add_f32_dpp v135, v135, v135 quad_perm:[2,3,0,1] row_mask:0xf bank_mask:0xf bound_ctrl:1
	v_pk_fma_f32 v[34:35], v[124:125], v[96:97], v[34:35] op_sel:[1,0,0]
	v_add_f32_dpp v134, v134, v134 row_half_mirror row_mask:0xf bank_mask:0xf bound_ctrl:1
	v_add_f32_dpp v135, v135, v135 row_half_mirror row_mask:0xf bank_mask:0xf bound_ctrl:1
	v_pk_fma_f32 v[32:33], v[126:127], v[96:97], v[32:33] op_sel_hi:[0,1,1]
	v_pk_fma_f32 v[90:91], v[126:127], v[96:97], v[90:91] op_sel:[1,0,0]
	v_add_f32_dpp v134, v134, v134 row_mirror row_mask:0xf bank_mask:0xf bound_ctrl:1
	v_add_f32_dpp v135, v135, v135 row_mirror row_mask:0xf bank_mask:0xf bound_ctrl:1
	v_pk_fma_f32 v[28:29], v[120:121], v[134:135], v[28:29] op_sel_hi:[0,1,1]
	v_pk_fma_f32 v[34:35], v[120:121], v[134:135], v[34:35] op_sel:[1,0,0]
	v_pk_fma_f32 v[32:33], v[122:123], v[134:135], v[32:33] op_sel_hi:[0,1,1]
	v_pk_fma_f32 v[90:91], v[122:123], v[134:135], v[90:91] op_sel:[1,0,0]
	s_waitcnt lgkmcnt(0)
	v_pk_mul_f32 v[134:135], v[28:29], v[24:25] op_sel_hi:[1,0]
	v_pk_mul_f32 v[116:117], v[28:29], v[130:131] op_sel_hi:[1,0]
	v_pk_fma_f32 v[134:135], v[34:35], v[24:25], v[134:135] op_sel:[0,1,0]
	v_pk_fma_f32 v[116:117], v[34:35], v[130:131], v[116:117] op_sel:[0,1,0]
	v_pk_fma_f32 v[134:135], v[32:33], v[26:27], v[134:135] op_sel_hi:[1,0,1]
	v_pk_fma_f32 v[116:117], v[32:33], v[132:133], v[116:117] op_sel_hi:[1,0,1]
	v_pk_fma_f32 v[134:135], v[90:91], v[26:27], v[134:135] op_sel:[0,1,0]
	v_pk_fma_f32 v[116:117], v[90:91], v[132:133], v[116:117] op_sel:[0,1,0]
	v_cvt_pk_f16_f32 v116, v116, v117
	v_add_f32_dpp v134, v134, v134 quad_perm:[1,0,3,2] row_mask:0xf bank_mask:0xf bound_ctrl:1
	v_add_f32_dpp v135, v135, v135 quad_perm:[1,0,3,2] row_mask:0xf bank_mask:0xf bound_ctrl:1
	ds_write2st64_b32 v42, v118, v116 offset0:32 offset1:36
	ds_read_b128 v[116:119], v93 offset:14848
	ds_read_b128 v[120:123], v93 offset:18944
	ds_read_b128 v[124:127], v93 offset:10752
	ds_read_b128 v[130:133], v93 offset:2560
	ds_read_b64 v[96:97], v92 offset:1280
	v_pk_fma_f32 v[28:29], v[20:21], v[30:31], v[28:29] op_sel_hi:[0,1,1]
	v_add_f32_dpp v134, v134, v134 quad_perm:[2,3,0,1] row_mask:0xf bank_mask:0xf bound_ctrl:1
	v_add_f32_dpp v135, v135, v135 quad_perm:[2,3,0,1] row_mask:0xf bank_mask:0xf bound_ctrl:1
	v_pk_fma_f32 v[34:35], v[20:21], v[30:31], v[34:35] op_sel:[1,0,0]
	v_add_f32_dpp v134, v134, v134 row_half_mirror row_mask:0xf bank_mask:0xf bound_ctrl:1
	v_add_f32_dpp v135, v135, v135 row_half_mirror row_mask:0xf bank_mask:0xf bound_ctrl:1
	v_pk_fma_f32 v[32:33], v[22:23], v[30:31], v[32:33] op_sel_hi:[0,1,1]
	v_pk_fma_f32 v[90:91], v[22:23], v[30:31], v[90:91] op_sel:[1,0,0]
	ds_read_b64 v[30:31], v95 offset:22016
	v_add_f32_dpp v134, v134, v134 row_mirror row_mask:0xf bank_mask:0xf bound_ctrl:1
	v_add_f32_dpp v135, v135, v135 row_mirror row_mask:0xf bank_mask:0xf bound_ctrl:1
	v_pk_fma_f32 v[28:29], v[16:17], v[134:135], v[28:29] op_sel_hi:[0,1,1]
	v_pk_fma_f32 v[34:35], v[16:17], v[134:135], v[34:35] op_sel:[1,0,0]
	v_pk_fma_f32 v[32:33], v[18:19], v[134:135], v[32:33] op_sel_hi:[0,1,1]
	v_pk_fma_f32 v[90:91], v[18:19], v[134:135], v[90:91] op_sel:[1,0,0]
	s_waitcnt lgkmcnt(1)
	v_pk_mul_f32 v[134:135], v[28:29], v[116:117] op_sel_hi:[1,0]
	v_pk_mul_f32 v[16:17], v[28:29], v[12:13] op_sel_hi:[1,0]
	v_pk_fma_f32 v[134:135], v[34:35], v[116:117], v[134:135] op_sel:[0,1,0]
	v_pk_fma_f32 v[16:17], v[34:35], v[12:13], v[16:17] op_sel:[0,1,0]
	v_pk_fma_f32 v[134:135], v[32:33], v[118:119], v[134:135] op_sel_hi:[1,0,1]
	v_pk_fma_f32 v[16:17], v[32:33], v[14:15], v[16:17] op_sel_hi:[1,0,1]
	v_pk_fma_f32 v[134:135], v[90:91], v[118:119], v[134:135] op_sel:[0,1,0]
	v_pk_fma_f32 v[16:17], v[90:91], v[14:15], v[16:17] op_sel:[0,1,0]
	v_cvt_pk_f16_f32 v118, v16, v17
	v_add_f32_dpp v134, v134, v134 quad_perm:[1,0,3,2] row_mask:0xf bank_mask:0xf bound_ctrl:1
	v_add_f32_dpp v135, v135, v135 quad_perm:[1,0,3,2] row_mask:0xf bank_mask:0xf bound_ctrl:1
	ds_read_b128 v[24:27], v94 offset:15360
	ds_read_b128 v[16:19], v94 offset:19456
	ds_read_b128 v[20:23], v94 offset:11264
	ds_read_b128 v[12:15], v94 offset:3072
	v_pk_fma_f32 v[28:29], v[124:125], v[96:97], v[28:29] op_sel_hi:[0,1,1]
	v_add_f32_dpp v134, v134, v134 quad_perm:[2,3,0,1] row_mask:0xf bank_mask:0xf bound_ctrl:1
	v_add_f32_dpp v135, v135, v135 quad_perm:[2,3,0,1] row_mask:0xf bank_mask:0xf bound_ctrl:1
	v_pk_fma_f32 v[34:35], v[124:125], v[96:97], v[34:35] op_sel:[1,0,0]
	v_add_f32_dpp v134, v134, v134 row_half_mirror row_mask:0xf bank_mask:0xf bound_ctrl:1
	v_add_f32_dpp v135, v135, v135 row_half_mirror row_mask:0xf bank_mask:0xf bound_ctrl:1
	v_pk_fma_f32 v[32:33], v[126:127], v[96:97], v[32:33] op_sel_hi:[0,1,1]
	v_pk_fma_f32 v[90:91], v[126:127], v[96:97], v[90:91] op_sel:[1,0,0]
	v_add_f32_dpp v134, v134, v134 row_mirror row_mask:0xf bank_mask:0xf bound_ctrl:1
	v_add_f32_dpp v135, v135, v135 row_mirror row_mask:0xf bank_mask:0xf bound_ctrl:1
	v_pk_fma_f32 v[28:29], v[120:121], v[134:135], v[28:29] op_sel_hi:[0,1,1]
	v_pk_fma_f32 v[34:35], v[120:121], v[134:135], v[34:35] op_sel:[1,0,0]
	v_pk_fma_f32 v[32:33], v[122:123], v[134:135], v[32:33] op_sel_hi:[0,1,1]
	v_pk_fma_f32 v[90:91], v[122:123], v[134:135], v[90:91] op_sel:[1,0,0]
	s_waitcnt lgkmcnt(0)
	v_pk_mul_f32 v[134:135], v[28:29], v[24:25] op_sel_hi:[1,0]
	v_pk_mul_f32 v[116:117], v[28:29], v[130:131] op_sel_hi:[1,0]
	v_pk_fma_f32 v[134:135], v[34:35], v[24:25], v[134:135] op_sel:[0,1,0]
	v_pk_fma_f32 v[116:117], v[34:35], v[130:131], v[116:117] op_sel:[0,1,0]
	v_pk_fma_f32 v[134:135], v[32:33], v[26:27], v[134:135] op_sel_hi:[1,0,1]
	v_pk_fma_f32 v[116:117], v[32:33], v[132:133], v[116:117] op_sel_hi:[1,0,1]
	v_pk_fma_f32 v[134:135], v[90:91], v[26:27], v[134:135] op_sel:[0,1,0]
	v_pk_fma_f32 v[116:117], v[90:91], v[132:133], v[116:117] op_sel:[0,1,0]
	v_cvt_pk_f16_f32 v116, v116, v117
	v_add_f32_dpp v134, v134, v134 quad_perm:[1,0,3,2] row_mask:0xf bank_mask:0xf bound_ctrl:1
	v_add_f32_dpp v135, v135, v135 quad_perm:[1,0,3,2] row_mask:0xf bank_mask:0xf bound_ctrl:1
	ds_write2st64_b32 v42, v118, v116 offset0:40 offset1:44
	ds_read_b128 v[116:119], v93 offset:15360
	ds_read_b128 v[120:123], v93 offset:19456
	ds_read_b128 v[124:127], v93 offset:11264
	ds_read_b128 v[130:133], v93 offset:3072
	ds_read_b64 v[96:97], v92 offset:1536
	v_pk_fma_f32 v[28:29], v[20:21], v[30:31], v[28:29] op_sel_hi:[0,1,1]
	v_add_f32_dpp v134, v134, v134 quad_perm:[2,3,0,1] row_mask:0xf bank_mask:0xf bound_ctrl:1
	v_add_f32_dpp v135, v135, v135 quad_perm:[2,3,0,1] row_mask:0xf bank_mask:0xf bound_ctrl:1
	v_pk_fma_f32 v[34:35], v[20:21], v[30:31], v[34:35] op_sel:[1,0,0]
	v_add_f32_dpp v134, v134, v134 row_half_mirror row_mask:0xf bank_mask:0xf bound_ctrl:1
	v_add_f32_dpp v135, v135, v135 row_half_mirror row_mask:0xf bank_mask:0xf bound_ctrl:1
	v_pk_fma_f32 v[32:33], v[22:23], v[30:31], v[32:33] op_sel_hi:[0,1,1]
	v_pk_fma_f32 v[90:91], v[22:23], v[30:31], v[90:91] op_sel:[1,0,0]
	ds_read_b64 v[30:31], v95 offset:22272
	v_add_f32_dpp v134, v134, v134 row_mirror row_mask:0xf bank_mask:0xf bound_ctrl:1
	v_add_f32_dpp v135, v135, v135 row_mirror row_mask:0xf bank_mask:0xf bound_ctrl:1
	v_pk_fma_f32 v[28:29], v[16:17], v[134:135], v[28:29] op_sel_hi:[0,1,1]
	v_pk_fma_f32 v[34:35], v[16:17], v[134:135], v[34:35] op_sel:[1,0,0]
	v_pk_fma_f32 v[32:33], v[18:19], v[134:135], v[32:33] op_sel_hi:[0,1,1]
	v_pk_fma_f32 v[90:91], v[18:19], v[134:135], v[90:91] op_sel:[1,0,0]
	s_waitcnt lgkmcnt(1)
	v_pk_mul_f32 v[134:135], v[28:29], v[116:117] op_sel_hi:[1,0]
	v_pk_mul_f32 v[16:17], v[28:29], v[12:13] op_sel_hi:[1,0]
	v_pk_fma_f32 v[134:135], v[34:35], v[116:117], v[134:135] op_sel:[0,1,0]
	v_pk_fma_f32 v[16:17], v[34:35], v[12:13], v[16:17] op_sel:[0,1,0]
	v_pk_fma_f32 v[134:135], v[32:33], v[118:119], v[134:135] op_sel_hi:[1,0,1]
	v_pk_fma_f32 v[16:17], v[32:33], v[14:15], v[16:17] op_sel_hi:[1,0,1]
	v_pk_fma_f32 v[134:135], v[90:91], v[118:119], v[134:135] op_sel:[0,1,0]
	v_pk_fma_f32 v[16:17], v[90:91], v[14:15], v[16:17] op_sel:[0,1,0]
	v_cvt_pk_f16_f32 v118, v16, v17
	v_add_f32_dpp v134, v134, v134 quad_perm:[1,0,3,2] row_mask:0xf bank_mask:0xf bound_ctrl:1
	v_add_f32_dpp v135, v135, v135 quad_perm:[1,0,3,2] row_mask:0xf bank_mask:0xf bound_ctrl:1
	ds_read_b128 v[24:27], v94 offset:15872
	ds_read_b128 v[16:19], v94 offset:19968
	ds_read_b128 v[20:23], v94 offset:11776
	ds_read_b128 v[12:15], v94 offset:3584
	v_pk_fma_f32 v[28:29], v[124:125], v[96:97], v[28:29] op_sel_hi:[0,1,1]
	v_add_f32_dpp v134, v134, v134 quad_perm:[2,3,0,1] row_mask:0xf bank_mask:0xf bound_ctrl:1
	v_add_f32_dpp v135, v135, v135 quad_perm:[2,3,0,1] row_mask:0xf bank_mask:0xf bound_ctrl:1
	v_pk_fma_f32 v[34:35], v[124:125], v[96:97], v[34:35] op_sel:[1,0,0]
	v_add_f32_dpp v134, v134, v134 row_half_mirror row_mask:0xf bank_mask:0xf bound_ctrl:1
	v_add_f32_dpp v135, v135, v135 row_half_mirror row_mask:0xf bank_mask:0xf bound_ctrl:1
	v_pk_fma_f32 v[32:33], v[126:127], v[96:97], v[32:33] op_sel_hi:[0,1,1]
	v_pk_fma_f32 v[90:91], v[126:127], v[96:97], v[90:91] op_sel:[1,0,0]
	v_add_f32_dpp v134, v134, v134 row_mirror row_mask:0xf bank_mask:0xf bound_ctrl:1
	v_add_f32_dpp v135, v135, v135 row_mirror row_mask:0xf bank_mask:0xf bound_ctrl:1
	v_pk_fma_f32 v[28:29], v[120:121], v[134:135], v[28:29] op_sel_hi:[0,1,1]
	v_pk_fma_f32 v[34:35], v[120:121], v[134:135], v[34:35] op_sel:[1,0,0]
	v_pk_fma_f32 v[32:33], v[122:123], v[134:135], v[32:33] op_sel_hi:[0,1,1]
	v_pk_fma_f32 v[90:91], v[122:123], v[134:135], v[90:91] op_sel:[1,0,0]
	s_waitcnt lgkmcnt(0)
	v_pk_mul_f32 v[134:135], v[28:29], v[24:25] op_sel_hi:[1,0]
	v_pk_mul_f32 v[116:117], v[28:29], v[130:131] op_sel_hi:[1,0]
	v_pk_fma_f32 v[134:135], v[34:35], v[24:25], v[134:135] op_sel:[0,1,0]
	v_pk_fma_f32 v[116:117], v[34:35], v[130:131], v[116:117] op_sel:[0,1,0]
	v_pk_fma_f32 v[134:135], v[32:33], v[26:27], v[134:135] op_sel_hi:[1,0,1]
	v_pk_fma_f32 v[116:117], v[32:33], v[132:133], v[116:117] op_sel_hi:[1,0,1]
	v_pk_fma_f32 v[134:135], v[90:91], v[26:27], v[134:135] op_sel:[0,1,0]
	v_pk_fma_f32 v[116:117], v[90:91], v[132:133], v[116:117] op_sel:[0,1,0]
	v_cvt_pk_f16_f32 v116, v116, v117
	v_add_f32_dpp v134, v134, v134 quad_perm:[1,0,3,2] row_mask:0xf bank_mask:0xf bound_ctrl:1
	v_add_f32_dpp v135, v135, v135 quad_perm:[1,0,3,2] row_mask:0xf bank_mask:0xf bound_ctrl:1
	ds_write2st64_b32 v42, v118, v116 offset0:48 offset1:52
	ds_read_b128 v[116:119], v93 offset:15872
	ds_read_b128 v[120:123], v93 offset:19968
	ds_read_b128 v[124:127], v93 offset:11776
	ds_read_b128 v[130:133], v93 offset:3584
	ds_read_b64 v[96:97], v92 offset:1792
	v_pk_fma_f32 v[28:29], v[20:21], v[30:31], v[28:29] op_sel_hi:[0,1,1]
	v_add_f32_dpp v134, v134, v134 quad_perm:[2,3,0,1] row_mask:0xf bank_mask:0xf bound_ctrl:1
	v_add_f32_dpp v135, v135, v135 quad_perm:[2,3,0,1] row_mask:0xf bank_mask:0xf bound_ctrl:1
	v_pk_fma_f32 v[34:35], v[20:21], v[30:31], v[34:35] op_sel:[1,0,0]
	v_add_f32_dpp v134, v134, v134 row_half_mirror row_mask:0xf bank_mask:0xf bound_ctrl:1
	v_add_f32_dpp v135, v135, v135 row_half_mirror row_mask:0xf bank_mask:0xf bound_ctrl:1
	v_pk_fma_f32 v[32:33], v[22:23], v[30:31], v[32:33] op_sel_hi:[0,1,1]
	v_pk_fma_f32 v[90:91], v[22:23], v[30:31], v[90:91] op_sel:[1,0,0]
	ds_read_b64 v[30:31], v95 offset:22272
	v_add_f32_dpp v134, v134, v134 row_mirror row_mask:0xf bank_mask:0xf bound_ctrl:1
	v_add_f32_dpp v135, v135, v135 row_mirror row_mask:0xf bank_mask:0xf bound_ctrl:1
	v_pk_fma_f32 v[28:29], v[16:17], v[134:135], v[28:29] op_sel_hi:[0,1,1]
	v_pk_fma_f32 v[34:35], v[16:17], v[134:135], v[34:35] op_sel:[1,0,0]
	v_pk_fma_f32 v[32:33], v[18:19], v[134:135], v[32:33] op_sel_hi:[0,1,1]
	v_pk_fma_f32 v[90:91], v[18:19], v[134:135], v[90:91] op_sel:[1,0,0]
	s_waitcnt lgkmcnt(1)
	v_pk_mul_f32 v[134:135], v[28:29], v[116:117] op_sel_hi:[1,0]
	v_pk_mul_f32 v[16:17], v[28:29], v[12:13] op_sel_hi:[1,0]
	v_pk_fma_f32 v[134:135], v[34:35], v[116:117], v[134:135] op_sel:[0,1,0]
	v_pk_fma_f32 v[16:17], v[34:35], v[12:13], v[16:17] op_sel:[0,1,0]
	v_pk_fma_f32 v[134:135], v[32:33], v[118:119], v[134:135] op_sel_hi:[1,0,1]
	v_pk_fma_f32 v[16:17], v[32:33], v[14:15], v[16:17] op_sel_hi:[1,0,1]
	v_pk_fma_f32 v[134:135], v[90:91], v[118:119], v[134:135] op_sel:[0,1,0]
	v_pk_fma_f32 v[16:17], v[90:91], v[14:15], v[16:17] op_sel:[0,1,0]
	v_cvt_pk_f16_f32 v118, v16, v17
	v_add_f32_dpp v134, v134, v134 quad_perm:[1,0,3,2] row_mask:0xf bank_mask:0xf bound_ctrl:1
	v_add_f32_dpp v135, v135, v135 quad_perm:[1,0,3,2] row_mask:0xf bank_mask:0xf bound_ctrl:1
	ds_read_b128 v[24:27], v94 offset:15872
	ds_read_b128 v[16:19], v94 offset:19968
	ds_read_b128 v[20:23], v94 offset:11776
	ds_read_b128 v[12:15], v94 offset:3584
	v_pk_fma_f32 v[28:29], v[124:125], v[96:97], v[28:29] op_sel_hi:[0,1,1]
	v_add_f32_dpp v134, v134, v134 quad_perm:[2,3,0,1] row_mask:0xf bank_mask:0xf bound_ctrl:1
	v_add_f32_dpp v135, v135, v135 quad_perm:[2,3,0,1] row_mask:0xf bank_mask:0xf bound_ctrl:1
	v_pk_fma_f32 v[34:35], v[124:125], v[96:97], v[34:35] op_sel:[1,0,0]
	v_add_f32_dpp v134, v134, v134 row_half_mirror row_mask:0xf bank_mask:0xf bound_ctrl:1
	v_add_f32_dpp v135, v135, v135 row_half_mirror row_mask:0xf bank_mask:0xf bound_ctrl:1
	v_pk_fma_f32 v[32:33], v[126:127], v[96:97], v[32:33] op_sel_hi:[0,1,1]
	v_pk_fma_f32 v[90:91], v[126:127], v[96:97], v[90:91] op_sel:[1,0,0]
	v_add_f32_dpp v134, v134, v134 row_mirror row_mask:0xf bank_mask:0xf bound_ctrl:1
	v_add_f32_dpp v135, v135, v135 row_mirror row_mask:0xf bank_mask:0xf bound_ctrl:1
	v_pk_fma_f32 v[28:29], v[120:121], v[134:135], v[28:29] op_sel_hi:[0,1,1]
	v_pk_fma_f32 v[34:35], v[120:121], v[134:135], v[34:35] op_sel:[1,0,0]
	v_pk_fma_f32 v[32:33], v[122:123], v[134:135], v[32:33] op_sel_hi:[0,1,1]
	v_pk_fma_f32 v[90:91], v[122:123], v[134:135], v[90:91] op_sel:[1,0,0]
	v_pk_mul_f32 v[116:117], v[28:29], v[130:131] op_sel_hi:[1,0]
	v_pk_fma_f32 v[116:117], v[34:35], v[130:131], v[116:117] op_sel:[0,1,0]
	v_pk_fma_f32 v[116:117], v[32:33], v[132:133], v[116:117] op_sel_hi:[1,0,1]
	v_pk_fma_f32 v[116:117], v[90:91], v[132:133], v[116:117] op_sel:[0,1,0]
	v_cvt_pk_f16_f32 v116, v116, v117
	ds_write2st64_b32 v42, v118, v116 offset0:56 offset1:60
	v_swap_b32 v29, v34
	v_swap_b32 v33, v90
	s_waitcnt vmcnt(4) lgkmcnt(1)
	v_cvt_f32_f16_sdwa v31, v72 dst_sel:DWORD dst_unused:UNUSED_PAD src0_sel:WORD_1
	v_cvt_f32_f16_e32 v30, v72
	v_cvt_f32_f16_sdwa v93, v73 dst_sel:DWORD dst_unused:UNUSED_PAD src0_sel:WORD_1
	v_cvt_f32_f16_e32 v92, v73
	s_waitcnt vmcnt(1)
	v_cvt_f32_f16_sdwa v17, v80 dst_sel:DWORD dst_unused:UNUSED_PAD src0_sel:WORD_1
	v_cvt_f32_f16_e32 v16, v80
	v_cvt_f32_f16_sdwa v19, v81 dst_sel:DWORD dst_unused:UNUSED_PAD src0_sel:WORD_1
	v_cvt_f32_f16_e32 v18, v81
	v_pk_mul_f32 v[22:23], v[0:1], v[30:31]
	v_pk_mul_f32 v[20:21], v[2:3], v[92:93]
	v_pk_mul_f32 v[96:97], v[22:23], v[22:23]
	ds_read_b128 v[12:15], v94 offset:7936
	v_pk_mul_f32 v[94:95], v[20:21], v[20:21]
	v_add_f32_e32 v42, v96, v97
	v_cvt_f32_f16_sdwa v25, v70 dst_sel:DWORD dst_unused:UNUSED_PAD src0_sel:WORD_1
	v_cvt_f32_f16_e32 v24, v70
	v_cvt_f32_f16_sdwa v27, v71 dst_sel:DWORD dst_unused:UNUSED_PAD src0_sel:WORD_1
	v_cvt_f32_f16_e32 v26, v71
	v_add_f32_e32 v42, v94, v42
	v_add_f32_e32 v42, v95, v42
	v_pk_add_f32 v[94:95], v[16:17], -1.0 op_sel_hi:[1,0]
	v_pk_add_f32 v[96:97], v[18:19], -1.0 op_sel_hi:[1,0]
	v_pk_fma_f32 v[94:95], v[4:5], v[94:95], 1.0 op_sel_hi:[1,1,0]
	v_pk_fma_f32 v[96:97], v[6:7], v[96:97], 1.0 op_sel_hi:[1,1,0]
	v_pk_mul_f32 v[94:95], v[30:31], v[94:95]
	v_pk_mul_f32 v[96:97], v[92:93], v[96:97]
	v_pk_mul_f32 v[30:31], v[24:25], v[94:95]
	v_pk_mul_f32 v[92:93], v[26:27], v[96:97]
	v_pk_mul_f32 v[30:31], v[8:9], v[30:31]
	v_pk_mul_f32 v[92:93], v[10:11], v[92:93]
	v_add_f32_e32 v30, v30, v31
	v_add_f32_e32 v31, v92, v93
	v_add_f32_e32 v30, v30, v31
	v_add_f32_dpp v42, v42, v42 quad_perm:[1,0,3,2] row_mask:0xf bank_mask:0xf bound_ctrl:1
	s_nop 0
	v_add_f32_dpp v30, v30, v30 quad_perm:[1,0,3,2] row_mask:0xf bank_mask:0xf bound_ctrl:1
	v_add_f32_dpp v42, v42, v42 quad_perm:[2,3,0,1] row_mask:0xf bank_mask:0xf bound_ctrl:1
	s_nop 0
	v_add_f32_dpp v30, v30, v30 quad_perm:[2,3,0,1] row_mask:0xf bank_mask:0xf bound_ctrl:1
	v_add_f32_dpp v42, v42, v42 row_half_mirror row_mask:0xf bank_mask:0xf bound_ctrl:1
	s_nop 0
	v_add_f32_dpp v30, v30, v30 row_half_mirror row_mask:0xf bank_mask:0xf bound_ctrl:1
	v_mov_b32_dpp v116, v42 row_mirror row_mask:0xf bank_mask:0xf bound_ctrl:1
	s_nop 0
	v_mov_b32_dpp v31, v30 row_mirror row_mask:0xf bank_mask:0xf bound_ctrl:1
	s_and_saveexec_b64 s[12:13], s[6:7]
	s_cbranch_execz .LBB0_430
	s_add_i32 s42, s95, 16
	v_cmp_lt_u32_e32 vcc, s42, v106
	s_and_b64 exec, exec, vcc
	s_cbranch_execz .LBB0_430
	v_add_f32_e32 v92, v30, v31
	v_add_u32_e32 v30, s42, v46
	v_ashrrev_i32_e32 v31, 31, v30
	v_lshlrev_b64 v[30:31], 6, v[30:31]
	v_lshl_add_u64 v[30:31], s[58:59], 0, v[30:31]
	global_store_dword v[30:31], v92, off

.LBB0_437:
	v_swap_b32 v93, v94
	v_swap_b32 v33, v34
	s_waitcnt lgkmcnt(0)
	v_pk_mul_f32 v[130:131], v[92:93], v[24:25] op_sel_hi:[1,0]
	v_pk_fma_f32 v[130:131], v[94:95], v[24:25], v[130:131] op_sel:[0,1,0]
	v_pk_fma_f32 v[130:131], v[32:33], v[26:27], v[130:131] op_sel_hi:[1,0,1]
	v_pk_fma_f32 v[130:131], v[34:35], v[26:27], v[130:131] op_sel:[0,1,0]
	ds_read_b128 v[12:15], v113 offset:12288
	ds_read_b128 v[116:119], v113 offset:16384
	ds_read_b128 v[120:123], v113 offset:8192
	ds_read_b128 v[124:127], v113
	ds_read_b64 v[90:91], v112
	v_pk_fma_f32 v[92:93], v[28:29], v[96:97], v[92:93] op_sel_hi:[0,1,1]
	v_pk_fma_f32 v[94:95], v[28:29], v[96:97], v[94:95] op_sel:[1,0,0]
	v_add_f32_dpp v130, v130, v130 quad_perm:[1,0,3,2] row_mask:0xf bank_mask:0xf bound_ctrl:1
	v_add_f32_dpp v131, v131, v131 quad_perm:[1,0,3,2] row_mask:0xf bank_mask:0xf bound_ctrl:1
	v_pk_fma_f32 v[32:33], v[30:31], v[96:97], v[32:33] op_sel_hi:[0,1,1]
	v_add_f32_dpp v130, v130, v130 quad_perm:[2,3,0,1] row_mask:0xf bank_mask:0xf bound_ctrl:1
	v_add_f32_dpp v131, v131, v131 quad_perm:[2,3,0,1] row_mask:0xf bank_mask:0xf bound_ctrl:1
	v_pk_fma_f32 v[34:35], v[30:31], v[96:97], v[34:35] op_sel:[1,0,0]
	v_add_f32_dpp v130, v130, v130 row_half_mirror row_mask:0xf bank_mask:0xf bound_ctrl:1
	v_add_f32_dpp v131, v131, v131 row_half_mirror row_mask:0xf bank_mask:0xf bound_ctrl:1
	ds_read_b64 v[96:97], v115 offset:20736
	v_add_f32_dpp v130, v130, v130 row_mirror row_mask:0xf bank_mask:0xf bound_ctrl:1
	v_add_f32_dpp v131, v131, v131 row_mirror row_mask:0xf bank_mask:0xf bound_ctrl:1
	v_pk_fma_f32 v[92:93], v[20:21], v[130:131], v[92:93] op_sel_hi:[0,1,1]
	v_pk_fma_f32 v[94:95], v[20:21], v[130:131], v[94:95] op_sel:[1,0,0]
	v_pk_fma_f32 v[32:33], v[22:23], v[130:131], v[32:33] op_sel_hi:[0,1,1]
	v_pk_fma_f32 v[34:35], v[22:23], v[130:131], v[34:35] op_sel:[1,0,0]
	s_waitcnt lgkmcnt(1)
	v_pk_mul_f32 v[130:131], v[92:93], v[12:13] op_sel_hi:[1,0]
	v_pk_mul_f32 v[20:21], v[92:93], v[16:17] op_sel_hi:[1,0]
	v_pk_fma_f32 v[130:131], v[94:95], v[12:13], v[130:131] op_sel:[0,1,0]
	v_pk_fma_f32 v[20:21], v[94:95], v[16:17], v[20:21] op_sel:[0,1,0]
	v_pk_fma_f32 v[130:131], v[32:33], v[14:15], v[130:131] op_sel_hi:[1,0,1]
	v_pk_fma_f32 v[20:21], v[32:33], v[18:19], v[20:21] op_sel_hi:[1,0,1]
	v_pk_fma_f32 v[130:131], v[34:35], v[14:15], v[130:131] op_sel:[0,1,0]
	v_pk_fma_f32 v[20:21], v[34:35], v[18:19], v[20:21] op_sel:[0,1,0]
	v_cvt_pk_f16_f32 v14, v20, v21
	v_add_f32_dpp v130, v130, v130 quad_perm:[1,0,3,2] row_mask:0xf bank_mask:0xf bound_ctrl:1
	v_add_f32_dpp v131, v131, v131 quad_perm:[1,0,3,2] row_mask:0xf bank_mask:0xf bound_ctrl:1
	ds_read_b128 v[24:27], v114 offset:12800
	ds_read_b128 v[20:23], v114 offset:16896
	ds_read_b128 v[28:31], v114 offset:8704
	ds_read_b128 v[16:19], v114 offset:512
	v_pk_fma_f32 v[92:93], v[120:121], v[90:91], v[92:93] op_sel_hi:[0,1,1]
	v_add_f32_dpp v130, v130, v130 quad_perm:[2,3,0,1] row_mask:0xf bank_mask:0xf bound_ctrl:1
	v_add_f32_dpp v131, v131, v131 quad_perm:[2,3,0,1] row_mask:0xf bank_mask:0xf bound_ctrl:1
	v_pk_fma_f32 v[94:95], v[120:121], v[90:91], v[94:95] op_sel:[1,0,0]
	v_add_f32_dpp v130, v130, v130 row_half_mirror row_mask:0xf bank_mask:0xf bound_ctrl:1
	v_add_f32_dpp v131, v131, v131 row_half_mirror row_mask:0xf bank_mask:0xf bound_ctrl:1
	v_pk_fma_f32 v[32:33], v[122:123], v[90:91], v[32:33] op_sel_hi:[0,1,1]
	v_pk_fma_f32 v[34:35], v[122:123], v[90:91], v[34:35] op_sel:[1,0,0]
	v_add_f32_dpp v130, v130, v130 row_mirror row_mask:0xf bank_mask:0xf bound_ctrl:1
	v_add_f32_dpp v131, v131, v131 row_mirror row_mask:0xf bank_mask:0xf bound_ctrl:1
	v_pk_fma_f32 v[92:93], v[116:117], v[130:131], v[92:93] op_sel_hi:[0,1,1]
	v_pk_fma_f32 v[94:95], v[116:117], v[130:131], v[94:95] op_sel:[1,0,0]
	v_pk_fma_f32 v[32:33], v[118:119], v[130:131], v[32:33] op_sel_hi:[0,1,1]
	v_pk_fma_f32 v[34:35], v[118:119], v[130:131], v[34:35] op_sel:[1,0,0]
	s_waitcnt lgkmcnt(0)
	v_pk_mul_f32 v[130:131], v[92:93], v[24:25] op_sel_hi:[1,0]
	v_pk_mul_f32 v[12:13], v[92:93], v[124:125] op_sel_hi:[1,0]
	v_pk_fma_f32 v[130:131], v[94:95], v[24:25], v[130:131] op_sel:[0,1,0]
	v_pk_fma_f32 v[12:13], v[94:95], v[124:125], v[12:13] op_sel:[0,1,0]
	v_pk_fma_f32 v[130:131], v[32:33], v[26:27], v[130:131] op_sel_hi:[1,0,1]
	v_pk_fma_f32 v[12:13], v[32:33], v[126:127], v[12:13] op_sel_hi:[1,0,1]
	v_pk_fma_f32 v[130:131], v[34:35], v[26:27], v[130:131] op_sel:[0,1,0]
	v_pk_fma_f32 v[12:13], v[34:35], v[126:127], v[12:13] op_sel:[0,1,0]
	v_cvt_pk_f16_f32 v12, v12, v13
	v_add_f32_dpp v130, v130, v130 quad_perm:[1,0,3,2] row_mask:0xf bank_mask:0xf bound_ctrl:1
	v_add_f32_dpp v131, v131, v131 quad_perm:[1,0,3,2] row_mask:0xf bank_mask:0xf bound_ctrl:1
	ds_write2st64_b32 v47, v14, v12 offset0:0 offset1:4
	ds_read_b128 v[12:15], v113 offset:12800
	ds_read_b128 v[116:119], v113 offset:16896
	ds_read_b128 v[120:123], v113 offset:8704
	ds_read_b128 v[124:127], v113 offset:512
	ds_read_b64 v[90:91], v112 offset:256
	v_pk_fma_f32 v[92:93], v[28:29], v[96:97], v[92:93] op_sel_hi:[0,1,1]
	v_add_f32_dpp v130, v130, v130 quad_perm:[2,3,0,1] row_mask:0xf bank_mask:0xf bound_ctrl:1
	v_add_f32_dpp v131, v131, v131 quad_perm:[2,3,0,1] row_mask:0xf bank_mask:0xf bound_ctrl:1
	v_pk_fma_f32 v[94:95], v[28:29], v[96:97], v[94:95] op_sel:[1,0,0]
	v_add_f32_dpp v130, v130, v130 row_half_mirror row_mask:0xf bank_mask:0xf bound_ctrl:1
	v_add_f32_dpp v131, v131, v131 row_half_mirror row_mask:0xf bank_mask:0xf bound_ctrl:1
	v_pk_fma_f32 v[32:33], v[30:31], v[96:97], v[32:33] op_sel_hi:[0,1,1]
	v_pk_fma_f32 v[34:35], v[30:31], v[96:97], v[34:35] op_sel:[1,0,0]
	ds_read_b64 v[96:97], v115 offset:20992
	v_add_f32_dpp v130, v130, v130 row_mirror row_mask:0xf bank_mask:0xf bound_ctrl:1
	v_add_f32_dpp v131, v131, v131 row_mirror row_mask:0xf bank_mask:0xf bound_ctrl:1
	v_pk_fma_f32 v[92:93], v[20:21], v[130:131], v[92:93] op_sel_hi:[0,1,1]
	v_pk_fma_f32 v[94:95], v[20:21], v[130:131], v[94:95] op_sel:[1,0,0]
	v_pk_fma_f32 v[32:33], v[22:23], v[130:131], v[32:33] op_sel_hi:[0,1,1]
	v_pk_fma_f32 v[34:35], v[22:23], v[130:131], v[34:35] op_sel:[1,0,0]
	s_waitcnt lgkmcnt(1)
	v_pk_mul_f32 v[130:131], v[92:93], v[12:13] op_sel_hi:[1,0]
	v_pk_mul_f32 v[20:21], v[92:93], v[16:17] op_sel_hi:[1,0]
	v_pk_fma_f32 v[130:131], v[94:95], v[12:13], v[130:131] op_sel:[0,1,0]
	v_pk_fma_f32 v[20:21], v[94:95], v[16:17], v[20:21] op_sel:[0,1,0]
	v_pk_fma_f32 v[130:131], v[32:33], v[14:15], v[130:131] op_sel_hi:[1,0,1]
	v_pk_fma_f32 v[20:21], v[32:33], v[18:19], v[20:21] op_sel_hi:[1,0,1]
	v_pk_fma_f32 v[130:131], v[34:35], v[14:15], v[130:131] op_sel:[0,1,0]
	v_pk_fma_f32 v[20:21], v[34:35], v[18:19], v[20:21] op_sel:[0,1,0]
	v_cvt_pk_f16_f32 v14, v20, v21
	v_add_f32_dpp v130, v130, v130 quad_perm:[1,0,3,2] row_mask:0xf bank_mask:0xf bound_ctrl:1
	v_add_f32_dpp v131, v131, v131 quad_perm:[1,0,3,2] row_mask:0xf bank_mask:0xf bound_ctrl:1
	ds_read_b128 v[24:27], v114 offset:13312
	ds_read_b128 v[20:23], v114 offset:17408
	ds_read_b128 v[28:31], v114 offset:9216
	ds_read_b128 v[16:19], v114 offset:1024
	v_pk_fma_f32 v[92:93], v[120:121], v[90:91], v[92:93] op_sel_hi:[0,1,1]
	v_add_f32_dpp v130, v130, v130 quad_perm:[2,3,0,1] row_mask:0xf bank_mask:0xf bound_ctrl:1
	v_add_f32_dpp v131, v131, v131 quad_perm:[2,3,0,1] row_mask:0xf bank_mask:0xf bound_ctrl:1
	v_pk_fma_f32 v[94:95], v[120:121], v[90:91], v[94:95] op_sel:[1,0,0]
	v_add_f32_dpp v130, v130, v130 row_half_mirror row_mask:0xf bank_mask:0xf bound_ctrl:1
	v_add_f32_dpp v131, v131, v131 row_half_mirror row_mask:0xf bank_mask:0xf bound_ctrl:1
	v_pk_fma_f32 v[32:33], v[122:123], v[90:91], v[32:33] op_sel_hi:[0,1,1]
	v_pk_fma_f32 v[34:35], v[122:123], v[90:91], v[34:35] op_sel:[1,0,0]
	v_add_f32_dpp v130, v130, v130 row_mirror row_mask:0xf bank_mask:0xf bound_ctrl:1
	v_add_f32_dpp v131, v131, v131 row_mirror row_mask:0xf bank_mask:0xf bound_ctrl:1
	v_pk_fma_f32 v[92:93], v[116:117], v[130:131], v[92:93] op_sel_hi:[0,1,1]
	v_pk_fma_f32 v[94:95], v[116:117], v[130:131], v[94:95] op_sel:[1,0,0]
	v_pk_fma_f32 v[32:33], v[118:119], v[130:131], v[32:33] op_sel_hi:[0,1,1]
	v_pk_fma_f32 v[34:35], v[118:119], v[130:131], v[34:35] op_sel:[1,0,0]
	s_waitcnt lgkmcnt(0)
	v_pk_mul_f32 v[130:131], v[92:93], v[24:25] op_sel_hi:[1,0]
	v_pk_mul_f32 v[12:13], v[92:93], v[124:125] op_sel_hi:[1,0]
	v_pk_fma_f32 v[130:131], v[94:95], v[24:25], v[130:131] op_sel:[0,1,0]
	v_pk_fma_f32 v[12:13], v[94:95], v[124:125], v[12:13] op_sel:[0,1,0]
	v_pk_fma_f32 v[130:131], v[32:33], v[26:27], v[130:131] op_sel_hi:[1,0,1]
	v_pk_fma_f32 v[12:13], v[32:33], v[126:127], v[12:13] op_sel_hi:[1,0,1]
	v_pk_fma_f32 v[130:131], v[34:35], v[26:27], v[130:131] op_sel:[0,1,0]
	v_pk_fma_f32 v[12:13], v[34:35], v[126:127], v[12:13] op_sel:[0,1,0]
	v_cvt_pk_f16_f32 v12, v12, v13
	v_add_f32_dpp v130, v130, v130 quad_perm:[1,0,3,2] row_mask:0xf bank_mask:0xf bound_ctrl:1
	v_add_f32_dpp v131, v131, v131 quad_perm:[1,0,3,2] row_mask:0xf bank_mask:0xf bound_ctrl:1
	ds_write2st64_b32 v47, v14, v12 offset0:8 offset1:12
	ds_read_b128 v[12:15], v113 offset:13312
	ds_read_b128 v[116:119], v113 offset:17408
	ds_read_b128 v[120:123], v113 offset:9216
	ds_read_b128 v[124:127], v113 offset:1024
	ds_read_b64 v[90:91], v112 offset:512
	v_pk_fma_f32 v[92:93], v[28:29], v[96:97], v[92:93] op_sel_hi:[0,1,1]
	v_add_f32_dpp v130, v130, v130 quad_perm:[2,3,0,1] row_mask:0xf bank_mask:0xf bound_ctrl:1
	v_add_f32_dpp v131, v131, v131 quad_perm:[2,3,0,1] row_mask:0xf bank_mask:0xf bound_ctrl:1
	v_pk_fma_f32 v[94:95], v[28:29], v[96:97], v[94:95] op_sel:[1,0,0]
	v_add_f32_dpp v130, v130, v130 row_half_mirror row_mask:0xf bank_mask:0xf bound_ctrl:1
	v_add_f32_dpp v131, v131, v131 row_half_mirror row_mask:0xf bank_mask:0xf bound_ctrl:1
	v_pk_fma_f32 v[32:33], v[30:31], v[96:97], v[32:33] op_sel_hi:[0,1,1]
	v_pk_fma_f32 v[34:35], v[30:31], v[96:97], v[34:35] op_sel:[1,0,0]
	ds_read_b64 v[96:97], v115 offset:21248
	v_add_f32_dpp v130, v130, v130 row_mirror row_mask:0xf bank_mask:0xf bound_ctrl:1
	v_add_f32_dpp v131, v131, v131 row_mirror row_mask:0xf bank_mask:0xf bound_ctrl:1
	v_pk_fma_f32 v[92:93], v[20:21], v[130:131], v[92:93] op_sel_hi:[0,1,1]
	v_pk_fma_f32 v[94:95], v[20:21], v[130:131], v[94:95] op_sel:[1,0,0]
	v_pk_fma_f32 v[32:33], v[22:23], v[130:131], v[32:33] op_sel_hi:[0,1,1]
	v_pk_fma_f32 v[34:35], v[22:23], v[130:131], v[34:35] op_sel:[1,0,0]
	s_waitcnt lgkmcnt(1)
	v_pk_mul_f32 v[130:131], v[92:93], v[12:13] op_sel_hi:[1,0]
	v_pk_mul_f32 v[20:21], v[92:93], v[16:17] op_sel_hi:[1,0]
	v_pk_fma_f32 v[130:131], v[94:95], v[12:13], v[130:131] op_sel:[0,1,0]
	v_pk_fma_f32 v[20:21], v[94:95], v[16:17], v[20:21] op_sel:[0,1,0]
	v_pk_fma_f32 v[130:131], v[32:33], v[14:15], v[130:131] op_sel_hi:[1,0,1]
	v_pk_fma_f32 v[20:21], v[32:33], v[18:19], v[20:21] op_sel_hi:[1,0,1]
	v_pk_fma_f32 v[130:131], v[34:35], v[14:15], v[130:131] op_sel:[0,1,0]
	v_pk_fma_f32 v[20:21], v[34:35], v[18:19], v[20:21] op_sel:[0,1,0]
	v_cvt_pk_f16_f32 v14, v20, v21
	v_add_f32_dpp v130, v130, v130 quad_perm:[1,0,3,2] row_mask:0xf bank_mask:0xf bound_ctrl:1
	v_add_f32_dpp v131, v131, v131 quad_perm:[1,0,3,2] row_mask:0xf bank_mask:0xf bound_ctrl:1
	ds_read_b128 v[24:27], v114 offset:13824
	ds_read_b128 v[20:23], v114 offset:17920
	ds_read_b128 v[28:31], v114 offset:9728
	ds_read_b128 v[16:19], v114 offset:1536
	v_pk_fma_f32 v[92:93], v[120:121], v[90:91], v[92:93] op_sel_hi:[0,1,1]
	v_add_f32_dpp v130, v130, v130 quad_perm:[2,3,0,1] row_mask:0xf bank_mask:0xf bound_ctrl:1
	v_add_f32_dpp v131, v131, v131 quad_perm:[2,3,0,1] row_mask:0xf bank_mask:0xf bound_ctrl:1
	v_pk_fma_f32 v[94:95], v[120:121], v[90:91], v[94:95] op_sel:[1,0,0]
	v_add_f32_dpp v130, v130, v130 row_half_mirror row_mask:0xf bank_mask:0xf bound_ctrl:1
	v_add_f32_dpp v131, v131, v131 row_half_mirror row_mask:0xf bank_mask:0xf bound_ctrl:1
	v_pk_fma_f32 v[32:33], v[122:123], v[90:91], v[32:33] op_sel_hi:[0,1,1]
	v_pk_fma_f32 v[34:35], v[122:123], v[90:91], v[34:35] op_sel:[1,0,0]
	v_add_f32_dpp v130, v130, v130 row_mirror row_mask:0xf bank_mask:0xf bound_ctrl:1
	v_add_f32_dpp v131, v131, v131 row_mirror row_mask:0xf bank_mask:0xf bound_ctrl:1
	v_pk_fma_f32 v[92:93], v[116:117], v[130:131], v[92:93] op_sel_hi:[0,1,1]
	v_pk_fma_f32 v[94:95], v[116:117], v[130:131], v[94:95] op_sel:[1,0,0]
	v_pk_fma_f32 v[32:33], v[118:119], v[130:131], v[32:33] op_sel_hi:[0,1,1]
	v_pk_fma_f32 v[34:35], v[118:119], v[130:131], v[34:35] op_sel:[1,0,0]
	s_waitcnt lgkmcnt(0)
	v_pk_mul_f32 v[130:131], v[92:93], v[24:25] op_sel_hi:[1,0]
	v_pk_mul_f32 v[12:13], v[92:93], v[124:125] op_sel_hi:[1,0]
	v_pk_fma_f32 v[130:131], v[94:95], v[24:25], v[130:131] op_sel:[0,1,0]
	v_pk_fma_f32 v[12:13], v[94:95], v[124:125], v[12:13] op_sel:[0,1,0]
	v_pk_fma_f32 v[130:131], v[32:33], v[26:27], v[130:131] op_sel_hi:[1,0,1]
	v_pk_fma_f32 v[12:13], v[32:33], v[126:127], v[12:13] op_sel_hi:[1,0,1]
	v_pk_fma_f32 v[130:131], v[34:35], v[26:27], v[130:131] op_sel:[0,1,0]
	v_pk_fma_f32 v[12:13], v[34:35], v[126:127], v[12:13] op_sel:[0,1,0]
	v_cvt_pk_f16_f32 v12, v12, v13
	v_add_f32_dpp v130, v130, v130 quad_perm:[1,0,3,2] row_mask:0xf bank_mask:0xf bound_ctrl:1
	v_add_f32_dpp v131, v131, v131 quad_perm:[1,0,3,2] row_mask:0xf bank_mask:0xf bound_ctrl:1
	ds_write2st64_b32 v47, v14, v12 offset0:16 offset1:20
	ds_read_b128 v[12:15], v113 offset:13824
	ds_read_b128 v[116:119], v113 offset:17920
	ds_read_b128 v[120:123], v113 offset:9728
	ds_read_b128 v[124:127], v113 offset:1536
	ds_read_b64 v[90:91], v112 offset:768
	v_pk_fma_f32 v[92:93], v[28:29], v[96:97], v[92:93] op_sel_hi:[0,1,1]
	v_add_f32_dpp v130, v130, v130 quad_perm:[2,3,0,1] row_mask:0xf bank_mask:0xf bound_ctrl:1
	v_add_f32_dpp v131, v131, v131 quad_perm:[2,3,0,1] row_mask:0xf bank_mask:0xf bound_ctrl:1
	v_pk_fma_f32 v[94:95], v[28:29], v[96:97], v[94:95] op_sel:[1,0,0]
	v_add_f32_dpp v130, v130, v130 row_half_mirror row_mask:0xf bank_mask:0xf bound_ctrl:1
	v_add_f32_dpp v131, v131, v131 row_half_mirror row_mask:0xf bank_mask:0xf bound_ctrl:1
	v_pk_fma_f32 v[32:33], v[30:31], v[96:97], v[32:33] op_sel_hi:[0,1,1]
	v_pk_fma_f32 v[34:35], v[30:31], v[96:97], v[34:35] op_sel:[1,0,0]
	ds_read_b64 v[96:97], v115 offset:21504
	v_add_f32_dpp v130, v130, v130 row_mirror row_mask:0xf bank_mask:0xf bound_ctrl:1
	v_add_f32_dpp v131, v131, v131 row_mirror row_mask:0xf bank_mask:0xf bound_ctrl:1
	v_pk_fma_f32 v[92:93], v[20:21], v[130:131], v[92:93] op_sel_hi:[0,1,1]
	v_pk_fma_f32 v[94:95], v[20:21], v[130:131], v[94:95] op_sel:[1,0,0]
	v_pk_fma_f32 v[32:33], v[22:23], v[130:131], v[32:33] op_sel_hi:[0,1,1]
	v_pk_fma_f32 v[34:35], v[22:23], v[130:131], v[34:35] op_sel:[1,0,0]
	s_waitcnt lgkmcnt(1)
	v_pk_mul_f32 v[130:131], v[92:93], v[12:13] op_sel_hi:[1,0]
	v_pk_mul_f32 v[20:21], v[92:93], v[16:17] op_sel_hi:[1,0]
	v_pk_fma_f32 v[130:131], v[94:95], v[12:13], v[130:131] op_sel:[0,1,0]
	v_pk_fma_f32 v[20:21], v[94:95], v[16:17], v[20:21] op_sel:[0,1,0]
	v_pk_fma_f32 v[130:131], v[32:33], v[14:15], v[130:131] op_sel_hi:[1,0,1]
	v_pk_fma_f32 v[20:21], v[32:33], v[18:19], v[20:21] op_sel_hi:[1,0,1]
	v_pk_fma_f32 v[130:131], v[34:35], v[14:15], v[130:131] op_sel:[0,1,0]
	v_pk_fma_f32 v[20:21], v[34:35], v[18:19], v[20:21] op_sel:[0,1,0]
	v_cvt_pk_f16_f32 v14, v20, v21
	v_add_f32_dpp v130, v130, v130 quad_perm:[1,0,3,2] row_mask:0xf bank_mask:0xf bound_ctrl:1
	v_add_f32_dpp v131, v131, v131 quad_perm:[1,0,3,2] row_mask:0xf bank_mask:0xf bound_ctrl:1
	ds_read_b128 v[24:27], v114 offset:14336
	ds_read_b128 v[20:23], v114 offset:18432
	ds_read_b128 v[28:31], v114 offset:10240
	ds_read_b128 v[16:19], v114 offset:2048
	v_pk_fma_f32 v[92:93], v[120:121], v[90:91], v[92:93] op_sel_hi:[0,1,1]
	v_add_f32_dpp v130, v130, v130 quad_perm:[2,3,0,1] row_mask:0xf bank_mask:0xf bound_ctrl:1
	v_add_f32_dpp v131, v131, v131 quad_perm:[2,3,0,1] row_mask:0xf bank_mask:0xf bound_ctrl:1
	v_pk_fma_f32 v[94:95], v[120:121], v[90:91], v[94:95] op_sel:[1,0,0]
	v_add_f32_dpp v130, v130, v130 row_half_mirror row_mask:0xf bank_mask:0xf bound_ctrl:1
	v_add_f32_dpp v131, v131, v131 row_half_mirror row_mask:0xf bank_mask:0xf bound_ctrl:1
	v_pk_fma_f32 v[32:33], v[122:123], v[90:91], v[32:33] op_sel_hi:[0,1,1]
	v_pk_fma_f32 v[34:35], v[122:123], v[90:91], v[34:35] op_sel:[1,0,0]
	v_add_f32_dpp v130, v130, v130 row_mirror row_mask:0xf bank_mask:0xf bound_ctrl:1
	v_add_f32_dpp v131, v131, v131 row_mirror row_mask:0xf bank_mask:0xf bound_ctrl:1
	v_pk_fma_f32 v[92:93], v[116:117], v[130:131], v[92:93] op_sel_hi:[0,1,1]
	v_pk_fma_f32 v[94:95], v[116:117], v[130:131], v[94:95] op_sel:[1,0,0]
	v_pk_fma_f32 v[32:33], v[118:119], v[130:131], v[32:33] op_sel_hi:[0,1,1]
	v_pk_fma_f32 v[34:35], v[118:119], v[130:131], v[34:35] op_sel:[1,0,0]
	s_waitcnt lgkmcnt(0)
	v_pk_mul_f32 v[130:131], v[92:93], v[24:25] op_sel_hi:[1,0]
	v_pk_mul_f32 v[12:13], v[92:93], v[124:125] op_sel_hi:[1,0]
	v_pk_fma_f32 v[130:131], v[94:95], v[24:25], v[130:131] op_sel:[0,1,0]
	v_pk_fma_f32 v[12:13], v[94:95], v[124:125], v[12:13] op_sel:[0,1,0]
	v_pk_fma_f32 v[130:131], v[32:33], v[26:27], v[130:131] op_sel_hi:[1,0,1]
	v_pk_fma_f32 v[12:13], v[32:33], v[126:127], v[12:13] op_sel_hi:[1,0,1]
	v_pk_fma_f32 v[130:131], v[34:35], v[26:27], v[130:131] op_sel:[0,1,0]
	v_pk_fma_f32 v[12:13], v[34:35], v[126:127], v[12:13] op_sel:[0,1,0]
	v_cvt_pk_f16_f32 v12, v12, v13
	v_add_f32_dpp v130, v130, v130 quad_perm:[1,0,3,2] row_mask:0xf bank_mask:0xf bound_ctrl:1
	v_add_f32_dpp v131, v131, v131 quad_perm:[1,0,3,2] row_mask:0xf bank_mask:0xf bound_ctrl:1
	ds_write2st64_b32 v47, v14, v12 offset0:24 offset1:28
	ds_read_b128 v[12:15], v113 offset:14336
	ds_read_b128 v[116:119], v113 offset:18432
	ds_read_b128 v[120:123], v113 offset:10240
	ds_read_b128 v[124:127], v113 offset:2048
	ds_read_b64 v[90:91], v112 offset:1024
	v_pk_fma_f32 v[92:93], v[28:29], v[96:97], v[92:93] op_sel_hi:[0,1,1]
	v_add_f32_dpp v130, v130, v130 quad_perm:[2,3,0,1] row_mask:0xf bank_mask:0xf bound_ctrl:1
	v_add_f32_dpp v131, v131, v131 quad_perm:[2,3,0,1] row_mask:0xf bank_mask:0xf bound_ctrl:1
	v_pk_fma_f32 v[94:95], v[28:29], v[96:97], v[94:95] op_sel:[1,0,0]
	v_add_f32_dpp v130, v130, v130 row_half_mirror row_mask:0xf bank_mask:0xf bound_ctrl:1
	v_add_f32_dpp v131, v131, v131 row_half_mirror row_mask:0xf bank_mask:0xf bound_ctrl:1
	v_pk_fma_f32 v[32:33], v[30:31], v[96:97], v[32:33] op_sel_hi:[0,1,1]
	v_pk_fma_f32 v[34:35], v[30:31], v[96:97], v[34:35] op_sel:[1,0,0]
	ds_read_b64 v[96:97], v115 offset:21760
	v_add_f32_dpp v130, v130, v130 row_mirror row_mask:0xf bank_mask:0xf bound_ctrl:1
	v_add_f32_dpp v131, v131, v131 row_mirror row_mask:0xf bank_mask:0xf bound_ctrl:1
	v_pk_fma_f32 v[92:93], v[20:21], v[130:131], v[92:93] op_sel_hi:[0,1,1]
	v_pk_fma_f32 v[94:95], v[20:21], v[130:131], v[94:95] op_sel:[1,0,0]
	v_pk_fma_f32 v[32:33], v[22:23], v[130:131], v[32:33] op_sel_hi:[0,1,1]
	v_pk_fma_f32 v[34:35], v[22:23], v[130:131], v[34:35] op_sel:[1,0,0]
	s_waitcnt lgkmcnt(1)
	v_pk_mul_f32 v[130:131], v[92:93], v[12:13] op_sel_hi:[1,0]
	v_pk_mul_f32 v[20:21], v[92:93], v[16:17] op_sel_hi:[1,0]
	v_pk_fma_f32 v[130:131], v[94:95], v[12:13], v[130:131] op_sel:[0,1,0]
	v_pk_fma_f32 v[20:21], v[94:95], v[16:17], v[20:21] op_sel:[0,1,0]
	v_pk_fma_f32 v[130:131], v[32:33], v[14:15], v[130:131] op_sel_hi:[1,0,1]
	v_pk_fma_f32 v[20:21], v[32:33], v[18:19], v[20:21] op_sel_hi:[1,0,1]
	v_pk_fma_f32 v[130:131], v[34:35], v[14:15], v[130:131] op_sel:[0,1,0]
	v_pk_fma_f32 v[20:21], v[34:35], v[18:19], v[20:21] op_sel:[0,1,0]
	v_cvt_pk_f16_f32 v14, v20, v21
	v_add_f32_dpp v130, v130, v130 quad_perm:[1,0,3,2] row_mask:0xf bank_mask:0xf bound_ctrl:1
	v_add_f32_dpp v131, v131, v131 quad_perm:[1,0,3,2] row_mask:0xf bank_mask:0xf bound_ctrl:1
	ds_read_b128 v[24:27], v114 offset:14848
	ds_read_b128 v[20:23], v114 offset:18944
	ds_read_b128 v[28:31], v114 offset:10752
	ds_read_b128 v[16:19], v114 offset:2560
	v_pk_fma_f32 v[92:93], v[120:121], v[90:91], v[92:93] op_sel_hi:[0,1,1]
	v_add_f32_dpp v130, v130, v130 quad_perm:[2,3,0,1] row_mask:0xf bank_mask:0xf bound_ctrl:1
	v_add_f32_dpp v131, v131, v131 quad_perm:[2,3,0,1] row_mask:0xf bank_mask:0xf bound_ctrl:1
	v_pk_fma_f32 v[94:95], v[120:121], v[90:91], v[94:95] op_sel:[1,0,0]
	v_add_f32_dpp v130, v130, v130 row_half_mirror row_mask:0xf bank_mask:0xf bound_ctrl:1
	v_add_f32_dpp v131, v131, v131 row_half_mirror row_mask:0xf bank_mask:0xf bound_ctrl:1
	v_pk_fma_f32 v[32:33], v[122:123], v[90:91], v[32:33] op_sel_hi:[0,1,1]
	v_pk_fma_f32 v[34:35], v[122:123], v[90:91], v[34:35] op_sel:[1,0,0]
	v_add_f32_dpp v130, v130, v130 row_mirror row_mask:0xf bank_mask:0xf bound_ctrl:1
	v_add_f32_dpp v131, v131, v131 row_mirror row_mask:0xf bank_mask:0xf bound_ctrl:1
	v_pk_fma_f32 v[92:93], v[116:117], v[130:131], v[92:93] op_sel_hi:[0,1,1]
	v_pk_fma_f32 v[94:95], v[116:117], v[130:131], v[94:95] op_sel:[1,0,0]
	v_pk_fma_f32 v[32:33], v[118:119], v[130:131], v[32:33] op_sel_hi:[0,1,1]
	v_pk_fma_f32 v[34:35], v[118:119], v[130:131], v[34:35] op_sel:[1,0,0]
	s_waitcnt lgkmcnt(0)
	v_pk_mul_f32 v[130:131], v[92:93], v[24:25] op_sel_hi:[1,0]
	v_pk_mul_f32 v[12:13], v[92:93], v[124:125] op_sel_hi:[1,0]
	v_pk_fma_f32 v[130:131], v[94:95], v[24:25], v[130:131] op_sel:[0,1,0]
	v_pk_fma_f32 v[12:13], v[94:95], v[124:125], v[12:13] op_sel:[0,1,0]
	v_pk_fma_f32 v[130:131], v[32:33], v[26:27], v[130:131] op_sel_hi:[1,0,1]
	v_pk_fma_f32 v[12:13], v[32:33], v[126:127], v[12:13] op_sel_hi:[1,0,1]
	v_pk_fma_f32 v[130:131], v[34:35], v[26:27], v[130:131] op_sel:[0,1,0]
	v_pk_fma_f32 v[12:13], v[34:35], v[126:127], v[12:13] op_sel:[0,1,0]
	v_cvt_pk_f16_f32 v12, v12, v13
	v_add_f32_dpp v130, v130, v130 quad_perm:[1,0,3,2] row_mask:0xf bank_mask:0xf bound_ctrl:1
	v_add_f32_dpp v131, v131, v131 quad_perm:[1,0,3,2] row_mask:0xf bank_mask:0xf bound_ctrl:1
	ds_write2st64_b32 v47, v14, v12 offset0:32 offset1:36
	ds_read_b128 v[12:15], v113 offset:14848
	ds_read_b128 v[116:119], v113 offset:18944
	ds_read_b128 v[120:123], v113 offset:10752
	ds_read_b128 v[124:127], v113 offset:2560
	ds_read_b64 v[90:91], v112 offset:1280
	v_pk_fma_f32 v[92:93], v[28:29], v[96:97], v[92:93] op_sel_hi:[0,1,1]
	v_add_f32_dpp v130, v130, v130 quad_perm:[2,3,0,1] row_mask:0xf bank_mask:0xf bound_ctrl:1
	v_add_f32_dpp v131, v131, v131 quad_perm:[2,3,0,1] row_mask:0xf bank_mask:0xf bound_ctrl:1
	v_pk_fma_f32 v[94:95], v[28:29], v[96:97], v[94:95] op_sel:[1,0,0]
	v_add_f32_dpp v130, v130, v130 row_half_mirror row_mask:0xf bank_mask:0xf bound_ctrl:1
	v_add_f32_dpp v131, v131, v131 row_half_mirror row_mask:0xf bank_mask:0xf bound_ctrl:1
	v_pk_fma_f32 v[32:33], v[30:31], v[96:97], v[32:33] op_sel_hi:[0,1,1]
	v_pk_fma_f32 v[34:35], v[30:31], v[96:97], v[34:35] op_sel:[1,0,0]
	ds_read_b64 v[96:97], v115 offset:22016
	v_add_f32_dpp v130, v130, v130 row_mirror row_mask:0xf bank_mask:0xf bound_ctrl:1
	v_add_f32_dpp v131, v131, v131 row_mirror row_mask:0xf bank_mask:0xf bound_ctrl:1
	v_pk_fma_f32 v[92:93], v[20:21], v[130:131], v[92:93] op_sel_hi:[0,1,1]
	v_pk_fma_f32 v[94:95], v[20:21], v[130:131], v[94:95] op_sel:[1,0,0]
	v_pk_fma_f32 v[32:33], v[22:23], v[130:131], v[32:33] op_sel_hi:[0,1,1]
	v_pk_fma_f32 v[34:35], v[22:23], v[130:131], v[34:35] op_sel:[1,0,0]
	s_waitcnt lgkmcnt(1)
	v_pk_mul_f32 v[130:131], v[92:93], v[12:13] op_sel_hi:[1,0]
	v_pk_mul_f32 v[20:21], v[92:93], v[16:17] op_sel_hi:[1,0]
	v_pk_fma_f32 v[130:131], v[94:95], v[12:13], v[130:131] op_sel:[0,1,0]
	v_pk_fma_f32 v[20:21], v[94:95], v[16:17], v[20:21] op_sel:[0,1,0]
	v_pk_fma_f32 v[130:131], v[32:33], v[14:15], v[130:131] op_sel_hi:[1,0,1]
	v_pk_fma_f32 v[20:21], v[32:33], v[18:19], v[20:21] op_sel_hi:[1,0,1]
	v_pk_fma_f32 v[130:131], v[34:35], v[14:15], v[130:131] op_sel:[0,1,0]
	v_pk_fma_f32 v[20:21], v[34:35], v[18:19], v[20:21] op_sel:[0,1,0]
	v_cvt_pk_f16_f32 v14, v20, v21
	v_add_f32_dpp v130, v130, v130 quad_perm:[1,0,3,2] row_mask:0xf bank_mask:0xf bound_ctrl:1
	v_add_f32_dpp v131, v131, v131 quad_perm:[1,0,3,2] row_mask:0xf bank_mask:0xf bound_ctrl:1
	ds_read_b128 v[24:27], v114 offset:15360
	ds_read_b128 v[20:23], v114 offset:19456
	ds_read_b128 v[28:31], v114 offset:11264
	ds_read_b128 v[16:19], v114 offset:3072
	v_pk_fma_f32 v[92:93], v[120:121], v[90:91], v[92:93] op_sel_hi:[0,1,1]
	v_add_f32_dpp v130, v130, v130 quad_perm:[2,3,0,1] row_mask:0xf bank_mask:0xf bound_ctrl:1
	v_add_f32_dpp v131, v131, v131 quad_perm:[2,3,0,1] row_mask:0xf bank_mask:0xf bound_ctrl:1
	v_pk_fma_f32 v[94:95], v[120:121], v[90:91], v[94:95] op_sel:[1,0,0]
	v_add_f32_dpp v130, v130, v130 row_half_mirror row_mask:0xf bank_mask:0xf bound_ctrl:1
	v_add_f32_dpp v131, v131, v131 row_half_mirror row_mask:0xf bank_mask:0xf bound_ctrl:1
	v_pk_fma_f32 v[32:33], v[122:123], v[90:91], v[32:33] op_sel_hi:[0,1,1]
	v_pk_fma_f32 v[34:35], v[122:123], v[90:91], v[34:35] op_sel:[1,0,0]
	v_add_f32_dpp v130, v130, v130 row_mirror row_mask:0xf bank_mask:0xf bound_ctrl:1
	v_add_f32_dpp v131, v131, v131 row_mirror row_mask:0xf bank_mask:0xf bound_ctrl:1
	v_pk_fma_f32 v[92:93], v[116:117], v[130:131], v[92:93] op_sel_hi:[0,1,1]
	v_pk_fma_f32 v[94:95], v[116:117], v[130:131], v[94:95] op_sel:[1,0,0]
	v_pk_fma_f32 v[32:33], v[118:119], v[130:131], v[32:33] op_sel_hi:[0,1,1]
	v_pk_fma_f32 v[34:35], v[118:119], v[130:131], v[34:35] op_sel:[1,0,0]
	s_waitcnt lgkmcnt(0)
	v_pk_mul_f32 v[130:131], v[92:93], v[24:25] op_sel_hi:[1,0]
	v_pk_mul_f32 v[12:13], v[92:93], v[124:125] op_sel_hi:[1,0]
	v_pk_fma_f32 v[130:131], v[94:95], v[24:25], v[130:131] op_sel:[0,1,0]
	v_pk_fma_f32 v[12:13], v[94:95], v[124:125], v[12:13] op_sel:[0,1,0]
	v_pk_fma_f32 v[130:131], v[32:33], v[26:27], v[130:131] op_sel_hi:[1,0,1]
	v_pk_fma_f32 v[12:13], v[32:33], v[126:127], v[12:13] op_sel_hi:[1,0,1]
	v_pk_fma_f32 v[130:131], v[34:35], v[26:27], v[130:131] op_sel:[0,1,0]
	v_pk_fma_f32 v[12:13], v[34:35], v[126:127], v[12:13] op_sel:[0,1,0]
	v_cvt_pk_f16_f32 v12, v12, v13
	v_add_f32_dpp v130, v130, v130 quad_perm:[1,0,3,2] row_mask:0xf bank_mask:0xf bound_ctrl:1
	v_add_f32_dpp v131, v131, v131 quad_perm:[1,0,3,2] row_mask:0xf bank_mask:0xf bound_ctrl:1
	ds_write2st64_b32 v47, v14, v12 offset0:40 offset1:44
	ds_read_b128 v[12:15], v113 offset:15360
	ds_read_b128 v[116:119], v113 offset:19456
	ds_read_b128 v[120:123], v113 offset:11264
	ds_read_b128 v[124:127], v113 offset:3072
	ds_read_b64 v[90:91], v112 offset:1536
	v_pk_fma_f32 v[92:93], v[28:29], v[96:97], v[92:93] op_sel_hi:[0,1,1]
	v_add_f32_dpp v130, v130, v130 quad_perm:[2,3,0,1] row_mask:0xf bank_mask:0xf bound_ctrl:1
	v_add_f32_dpp v131, v131, v131 quad_perm:[2,3,0,1] row_mask:0xf bank_mask:0xf bound_ctrl:1
	v_pk_fma_f32 v[94:95], v[28:29], v[96:97], v[94:95] op_sel:[1,0,0]
	v_add_f32_dpp v130, v130, v130 row_half_mirror row_mask:0xf bank_mask:0xf bound_ctrl:1
	v_add_f32_dpp v131, v131, v131 row_half_mirror row_mask:0xf bank_mask:0xf bound_ctrl:1
	v_pk_fma_f32 v[32:33], v[30:31], v[96:97], v[32:33] op_sel_hi:[0,1,1]
	v_pk_fma_f32 v[34:35], v[30:31], v[96:97], v[34:35] op_sel:[1,0,0]
	ds_read_b64 v[96:97], v115 offset:22272
	v_add_f32_dpp v130, v130, v130 row_mirror row_mask:0xf bank_mask:0xf bound_ctrl:1
	v_add_f32_dpp v131, v131, v131 row_mirror row_mask:0xf bank_mask:0xf bound_ctrl:1
	v_pk_fma_f32 v[92:93], v[20:21], v[130:131], v[92:93] op_sel_hi:[0,1,1]
	v_pk_fma_f32 v[94:95], v[20:21], v[130:131], v[94:95] op_sel:[1,0,0]
	v_pk_fma_f32 v[32:33], v[22:23], v[130:131], v[32:33] op_sel_hi:[0,1,1]
	v_pk_fma_f32 v[34:35], v[22:23], v[130:131], v[34:35] op_sel:[1,0,0]
	s_waitcnt lgkmcnt(1)
	v_pk_mul_f32 v[130:131], v[92:93], v[12:13] op_sel_hi:[1,0]
	v_pk_mul_f32 v[20:21], v[92:93], v[16:17] op_sel_hi:[1,0]
	v_pk_fma_f32 v[130:131], v[94:95], v[12:13], v[130:131] op_sel:[0,1,0]
	v_pk_fma_f32 v[20:21], v[94:95], v[16:17], v[20:21] op_sel:[0,1,0]
	v_pk_fma_f32 v[130:131], v[32:33], v[14:15], v[130:131] op_sel_hi:[1,0,1]
	v_pk_fma_f32 v[20:21], v[32:33], v[18:19], v[20:21] op_sel_hi:[1,0,1]
	v_pk_fma_f32 v[130:131], v[34:35], v[14:15], v[130:131] op_sel:[0,1,0]
	v_pk_fma_f32 v[20:21], v[34:35], v[18:19], v[20:21] op_sel:[0,1,0]
	v_cvt_pk_f16_f32 v14, v20, v21
	v_add_f32_dpp v130, v130, v130 quad_perm:[1,0,3,2] row_mask:0xf bank_mask:0xf bound_ctrl:1
	v_add_f32_dpp v131, v131, v131 quad_perm:[1,0,3,2] row_mask:0xf bank_mask:0xf bound_ctrl:1
	ds_read_b128 v[24:27], v114 offset:15872
	ds_read_b128 v[20:23], v114 offset:19968
	ds_read_b128 v[28:31], v114 offset:11776
	ds_read_b128 v[16:19], v114 offset:3584
	v_pk_fma_f32 v[92:93], v[120:121], v[90:91], v[92:93] op_sel_hi:[0,1,1]
	v_add_f32_dpp v130, v130, v130 quad_perm:[2,3,0,1] row_mask:0xf bank_mask:0xf bound_ctrl:1
	v_add_f32_dpp v131, v131, v131 quad_perm:[2,3,0,1] row_mask:0xf bank_mask:0xf bound_ctrl:1
	v_pk_fma_f32 v[94:95], v[120:121], v[90:91], v[94:95] op_sel:[1,0,0]
	v_add_f32_dpp v130, v130, v130 row_half_mirror row_mask:0xf bank_mask:0xf bound_ctrl:1
	v_add_f32_dpp v131, v131, v131 row_half_mirror row_mask:0xf bank_mask:0xf bound_ctrl:1
	v_pk_fma_f32 v[32:33], v[122:123], v[90:91], v[32:33] op_sel_hi:[0,1,1]
	v_pk_fma_f32 v[34:35], v[122:123], v[90:91], v[34:35] op_sel:[1,0,0]
	v_add_f32_dpp v130, v130, v130 row_mirror row_mask:0xf bank_mask:0xf bound_ctrl:1
	v_add_f32_dpp v131, v131, v131 row_mirror row_mask:0xf bank_mask:0xf bound_ctrl:1
	v_pk_fma_f32 v[92:93], v[116:117], v[130:131], v[92:93] op_sel_hi:[0,1,1]
	v_pk_fma_f32 v[94:95], v[116:117], v[130:131], v[94:95] op_sel:[1,0,0]
	v_pk_fma_f32 v[32:33], v[118:119], v[130:131], v[32:33] op_sel_hi:[0,1,1]
	v_pk_fma_f32 v[34:35], v[118:119], v[130:131], v[34:35] op_sel:[1,0,0]
	s_waitcnt lgkmcnt(0)
	v_pk_mul_f32 v[130:131], v[92:93], v[24:25] op_sel_hi:[1,0]
	v_pk_mul_f32 v[12:13], v[92:93], v[124:125] op_sel_hi:[1,0]
	v_pk_fma_f32 v[130:131], v[94:95], v[24:25], v[130:131] op_sel:[0,1,0]
	v_pk_fma_f32 v[12:13], v[94:95], v[124:125], v[12:13] op_sel:[0,1,0]
	v_pk_fma_f32 v[130:131], v[32:33], v[26:27], v[130:131] op_sel_hi:[1,0,1]
	v_pk_fma_f32 v[12:13], v[32:33], v[126:127], v[12:13] op_sel_hi:[1,0,1]
	v_pk_fma_f32 v[130:131], v[34:35], v[26:27], v[130:131] op_sel:[0,1,0]
	v_pk_fma_f32 v[12:13], v[34:35], v[126:127], v[12:13] op_sel:[0,1,0]
	v_cvt_pk_f16_f32 v12, v12, v13
	v_add_f32_dpp v130, v130, v130 quad_perm:[1,0,3,2] row_mask:0xf bank_mask:0xf bound_ctrl:1
	v_add_f32_dpp v131, v131, v131 quad_perm:[1,0,3,2] row_mask:0xf bank_mask:0xf bound_ctrl:1
	ds_write2st64_b32 v47, v14, v12 offset0:48 offset1:52
	ds_read_b128 v[12:15], v113 offset:15872
	ds_read_b128 v[116:119], v113 offset:19968
	ds_read_b128 v[120:123], v113 offset:11776
	ds_read_b128 v[124:127], v113 offset:3584
	ds_read_b64 v[90:91], v112 offset:1792
	v_pk_fma_f32 v[92:93], v[28:29], v[96:97], v[92:93] op_sel_hi:[0,1,1]
	v_add_f32_dpp v130, v130, v130 quad_perm:[2,3,0,1] row_mask:0xf bank_mask:0xf bound_ctrl:1
	v_add_f32_dpp v131, v131, v131 quad_perm:[2,3,0,1] row_mask:0xf bank_mask:0xf bound_ctrl:1
	v_pk_fma_f32 v[94:95], v[28:29], v[96:97], v[94:95] op_sel:[1,0,0]
	v_add_f32_dpp v130, v130, v130 row_half_mirror row_mask:0xf bank_mask:0xf bound_ctrl:1
	v_add_f32_dpp v131, v131, v131 row_half_mirror row_mask:0xf bank_mask:0xf bound_ctrl:1
	v_pk_fma_f32 v[32:33], v[30:31], v[96:97], v[32:33] op_sel_hi:[0,1,1]
	v_pk_fma_f32 v[34:35], v[30:31], v[96:97], v[34:35] op_sel:[1,0,0]
	ds_read_b64 v[96:97], v115 offset:22272
	v_add_f32_dpp v130, v130, v130 row_mirror row_mask:0xf bank_mask:0xf bound_ctrl:1
	v_add_f32_dpp v131, v131, v131 row_mirror row_mask:0xf bank_mask:0xf bound_ctrl:1
	v_pk_fma_f32 v[92:93], v[20:21], v[130:131], v[92:93] op_sel_hi:[0,1,1]
	v_pk_fma_f32 v[94:95], v[20:21], v[130:131], v[94:95] op_sel:[1,0,0]
	v_pk_fma_f32 v[32:33], v[22:23], v[130:131], v[32:33] op_sel_hi:[0,1,1]
	v_pk_fma_f32 v[34:35], v[22:23], v[130:131], v[34:35] op_sel:[1,0,0]
	s_waitcnt lgkmcnt(1)
	v_pk_mul_f32 v[130:131], v[92:93], v[12:13] op_sel_hi:[1,0]
	v_pk_mul_f32 v[20:21], v[92:93], v[16:17] op_sel_hi:[1,0]
	v_pk_fma_f32 v[130:131], v[94:95], v[12:13], v[130:131] op_sel:[0,1,0]
	v_pk_fma_f32 v[20:21], v[94:95], v[16:17], v[20:21] op_sel:[0,1,0]
	v_pk_fma_f32 v[130:131], v[32:33], v[14:15], v[130:131] op_sel_hi:[1,0,1]
	v_pk_fma_f32 v[20:21], v[32:33], v[18:19], v[20:21] op_sel_hi:[1,0,1]
	v_pk_fma_f32 v[130:131], v[34:35], v[14:15], v[130:131] op_sel:[0,1,0]
	v_pk_fma_f32 v[20:21], v[34:35], v[18:19], v[20:21] op_sel:[0,1,0]
	v_cvt_pk_f16_f32 v14, v20, v21
	v_add_f32_dpp v130, v130, v130 quad_perm:[1,0,3,2] row_mask:0xf bank_mask:0xf bound_ctrl:1
	v_add_f32_dpp v131, v131, v131 quad_perm:[1,0,3,2] row_mask:0xf bank_mask:0xf bound_ctrl:1
	ds_read_b128 v[24:27], v114 offset:15872
	ds_read_b128 v[20:23], v114 offset:19968
	ds_read_b128 v[28:31], v114 offset:11776
	ds_read_b128 v[16:19], v114 offset:3584
	v_pk_fma_f32 v[92:93], v[120:121], v[90:91], v[92:93] op_sel_hi:[0,1,1]
	v_add_f32_dpp v130, v130, v130 quad_perm:[2,3,0,1] row_mask:0xf bank_mask:0xf bound_ctrl:1
	v_add_f32_dpp v131, v131, v131 quad_perm:[2,3,0,1] row_mask:0xf bank_mask:0xf bound_ctrl:1
	v_pk_fma_f32 v[94:95], v[120:121], v[90:91], v[94:95] op_sel:[1,0,0]
	v_add_f32_dpp v130, v130, v130 row_half_mirror row_mask:0xf bank_mask:0xf bound_ctrl:1
	v_add_f32_dpp v131, v131, v131 row_half_mirror row_mask:0xf bank_mask:0xf bound_ctrl:1
	v_pk_fma_f32 v[32:33], v[122:123], v[90:91], v[32:33] op_sel_hi:[0,1,1]
	v_pk_fma_f32 v[34:35], v[122:123], v[90:91], v[34:35] op_sel:[1,0,0]
	v_add_f32_dpp v130, v130, v130 row_mirror row_mask:0xf bank_mask:0xf bound_ctrl:1
	v_add_f32_dpp v131, v131, v131 row_mirror row_mask:0xf bank_mask:0xf bound_ctrl:1
	v_pk_fma_f32 v[92:93], v[116:117], v[130:131], v[92:93] op_sel_hi:[0,1,1]
	v_pk_fma_f32 v[94:95], v[116:117], v[130:131], v[94:95] op_sel:[1,0,0]
	v_pk_fma_f32 v[32:33], v[118:119], v[130:131], v[32:33] op_sel_hi:[0,1,1]
	v_pk_fma_f32 v[34:35], v[118:119], v[130:131], v[34:35] op_sel:[1,0,0]
	v_pk_mul_f32 v[12:13], v[92:93], v[124:125] op_sel_hi:[1,0]
	v_pk_fma_f32 v[12:13], v[94:95], v[124:125], v[12:13] op_sel:[0,1,0]
	v_pk_fma_f32 v[12:13], v[32:33], v[126:127], v[12:13] op_sel_hi:[1,0,1]
	v_pk_fma_f32 v[12:13], v[34:35], v[126:127], v[12:13] op_sel:[0,1,0]
	v_cvt_pk_f16_f32 v12, v12, v13
	ds_write2st64_b32 v47, v14, v12 offset0:56 offset1:60
	v_swap_b32 v93, v94
	v_swap_b32 v33, v34
	ds_read_b128 v[12:15], v114 offset:7936
	s_add_i32 s93, s93, 3
	s_and_b64 vcc, exec, s[82:83]
	s_cbranch_vccz .LBB0_409
	s_waitcnt lgkmcnt(4)
	v_cvt_f32_f16_sdwa v29, v50 dst_sel:DWORD dst_unused:UNUSED_PAD src0_sel:WORD_1
	v_cvt_f32_f16_e32 v28, v50
	v_cvt_f32_f16_sdwa v31, v51 dst_sel:DWORD dst_unused:UNUSED_PAD src0_sel:WORD_1
	v_cvt_f32_f16_e32 v30, v51
	s_waitcnt lgkmcnt(3)
	v_cvt_f32_f16_sdwa v17, v56 dst_sel:DWORD dst_unused:UNUSED_PAD src0_sel:WORD_1
	v_cvt_f32_f16_e32 v16, v56
	v_cvt_f32_f16_sdwa v19, v57 dst_sel:DWORD dst_unused:UNUSED_PAD src0_sel:WORD_1
	v_cvt_f32_f16_e32 v18, v57
	v_pk_mul_f32 v[22:23], v[0:1], v[28:29]
	v_pk_mul_f32 v[20:21], v[2:3], v[30:31]
	s_waitcnt lgkmcnt(2)
	v_pk_mul_f32 v[96:97], v[22:23], v[22:23]
	v_pk_mul_f32 v[90:91], v[20:21], v[20:21]
	v_add_f32_e32 v42, v96, v97
	v_cvt_f32_f16_sdwa v25, v48 dst_sel:DWORD dst_unused:UNUSED_PAD src0_sel:WORD_1
	v_cvt_f32_f16_e32 v24, v48
	v_cvt_f32_f16_sdwa v27, v49 dst_sel:DWORD dst_unused:UNUSED_PAD src0_sel:WORD_1
	v_cvt_f32_f16_e32 v26, v49
	v_add_f32_e32 v42, v90, v42
	v_add_f32_e32 v42, v91, v42
	v_pk_add_f32 v[90:91], v[16:17], -1.0 op_sel_hi:[1,0]
	v_pk_add_f32 v[96:97], v[18:19], -1.0 op_sel_hi:[1,0]
	v_pk_fma_f32 v[90:91], v[4:5], v[90:91], 1.0 op_sel_hi:[1,1,0]
	v_pk_fma_f32 v[96:97], v[6:7], v[96:97], 1.0 op_sel_hi:[1,1,0]
	v_pk_mul_f32 v[90:91], v[28:29], v[90:91]
	v_pk_mul_f32 v[96:97], v[30:31], v[96:97]
	v_pk_mul_f32 v[28:29], v[24:25], v[90:91]
	v_pk_mul_f32 v[30:31], v[26:27], v[96:97]
	v_pk_mul_f32 v[28:29], v[8:9], v[28:29]
	v_pk_mul_f32 v[30:31], v[10:11], v[30:31]
	v_add_f32_e32 v28, v28, v29
	v_add_f32_e32 v29, v30, v31
	v_add_f32_e32 v28, v28, v29
	v_add_f32_dpp v42, v42, v42 quad_perm:[1,0,3,2] row_mask:0xf bank_mask:0xf bound_ctrl:1
	s_nop 0
	v_add_f32_dpp v28, v28, v28 quad_perm:[1,0,3,2] row_mask:0xf bank_mask:0xf bound_ctrl:1
	v_add_f32_dpp v42, v42, v42 quad_perm:[2,3,0,1] row_mask:0xf bank_mask:0xf bound_ctrl:1
	s_nop 0
	v_add_f32_dpp v28, v28, v28 quad_perm:[2,3,0,1] row_mask:0xf bank_mask:0xf bound_ctrl:1
	v_add_f32_dpp v42, v42, v42 row_half_mirror row_mask:0xf bank_mask:0xf bound_ctrl:1
	s_nop 0
	v_add_f32_dpp v28, v28, v28 row_half_mirror row_mask:0xf bank_mask:0xf bound_ctrl:1
	v_mov_b32_dpp v47, v42 row_mirror row_mask:0xf bank_mask:0xf bound_ctrl:1
	s_nop 0
	v_mov_b32_dpp v29, v28 row_mirror row_mask:0xf bank_mask:0xf bound_ctrl:1
	s_and_saveexec_b64 s[12:13], s[6:7]
	s_cbranch_execz .LBB0_442
	s_add_i32 s94, s94, 48
	v_cmp_lt_u32_e32 vcc, s94, v106
	s_and_b64 exec, exec, vcc
	s_cbranch_execz .LBB0_442
	v_add_f32_e32 v30, v28, v29
	v_add_u32_e32 v28, s94, v46
	v_ashrrev_i32_e32 v29, 31, v28
	v_lshlrev_b64 v[28:29], 6, v[28:29]
	v_lshl_add_u64 v[28:29], s[58:59], 0, v[28:29]
	global_store_dword v[28:29], v30, off
